# non-temporal (nt) loads on the read-once full-line streams: x rows in P0 and in the out-projection epilogue, the f32 weight reads of every transpose / conversion, the chunk states read by the state sc
# speedup vs baseline: 1.0226x; 1.0226x over previous
; #define LAS __attribute__((address_space(3)))
; __device__ __forceinline__ void transpose_item(const float* W, int K, int N, bf16* WT, const float* gain, LAS float* scr, int item, int nblk, int lane) {
;     const int kb = item / nblk, nb = item % nblk, k0 = 64 * kb, n0 = 64 * nb;
;     const int kr = lane >> 4, nc = 4 * (lane & 15);
;     const bool ok = (n0 + nc) < N;
;     f32x4 v[16];
; #pragma unroll
;     for (int i = 0; i < 16; ++i) { v[i] = (f32x4){0.f, 0.f, 0.f, 0.f}; if (ok) v[i] = *(const f32x4*)(W + (size_t)(k0 + 4 * i + kr) * N + n0 + nc); }
;     if (gain) {
; #pragma unroll
;         for (int i = 0; i < 16; ++i) v[i] = v[i] * gain[k0 + 4 * i + kr]; }
; __device__ __forceinline__ void p0_prologue(const Args& a, LAS unsigned char* lds) {
;     ...
;         if (r < I_OUT) { transpose_item(a.w_out, D_, D_, (bf16*)(ws + WS_WOUT), (64 * (r / (D_ / 64)) < 512) ? a.attn_out_g : a.ssm_norm_g - 512, scr, r, D_ / 64, lane); continue; } r -= I_OUT;
.LBB0_9:
	s_movk_i32 s4, 0x1ff
	v_cmp_lt_i32_e32 vcc, s4, v110
	s_and_saveexec_b64 s[4:5], vcc
	s_xor_b64 s[14:15], exec, s[4:5]
	s_cbranch_execz .LBB0_57
	s_movk_i32 s4, 0x22f
	v_cmp_lt_u32_e32 vcc, s4, v110
	s_and_saveexec_b64 s[4:5], vcc
	s_xor_b64 s[18:19], exec, s[4:5]
	s_cbranch_execz .LBB0_52
	s_movk_i32 s4, 0x24f
	v_cmp_lt_u32_e32 vcc, s4, v110
	s_and_saveexec_b64 s[4:5], vcc
	s_xor_b64 s[4:5], exec, s[4:5]
	s_cbranch_execz .LBB0_15
	v_and_b32_e32 v90, 0x3c0, v107
	v_and_b32_e32 v3, 0x3c0, v106
	v_or_b32_e32 v88, v90, v71
	v_lshlrev_b32_e32 v4, 2, v3
	v_mov_b32_e32 v5, v2
	v_lshl_add_u64 v[4:5], v[80:81], 0, v[4:5]
	v_lshlrev_b32_e32 v6, 12, v88
	v_mov_b32_e32 v7, v2
	v_lshl_add_u64 v[60:61], v[4:5], 0, v[6:7]
	s_movk_i32 s22, 0x4000
	v_add_co_u32_e32 v4, vcc, s22, v60
	s_mov_b32 s22, 0x8000
	s_nop 0
	v_addc_co_u32_e32 v5, vcc, 0, v61, vcc
	v_add_co_u32_e32 v12, vcc, s22, v60
	s_mov_b32 s22, 0x10000
	s_nop 0
	v_addc_co_u32_e32 v13, vcc, 0, v61, vcc
	v_add_co_u32_e32 v14, vcc, s41, v60
	global_load_dwordx4 v[8:11], v[60:61], off nt
	s_nop 0
	global_load_dwordx4 v[4:7], v[4:5], off nt
	v_addc_co_u32_e32 v15, vcc, 0, v61, vcc
	v_add_co_u32_e32 v20, vcc, s22, v60
	s_mov_b32 s22, 0x14000
	s_nop 0
	v_addc_co_u32_e32 v21, vcc, 0, v61, vcc
	v_add_co_u32_e32 v22, vcc, s22, v60
	s_mov_b32 s22, 0x1c000
	s_nop 0
	v_addc_co_u32_e32 v23, vcc, 0, v61, vcc
	v_add_co_u32_e32 v28, vcc, s43, v60
	global_load_dwordx4 v[16:19], v[12:13], off nt
	s_nop 0
	global_load_dwordx4 v[12:15], v[14:15], off nt
	v_addc_co_u32_e32 v29, vcc, 0, v61, vcc
	v_add_co_u32_e32 v30, vcc, s22, v60
	global_load_dwordx4 v[24:27], v[20:21], off nt
	s_nop 0
	global_load_dwordx4 v[20:23], v[22:23], off nt
	v_addc_co_u32_e32 v31, vcc, 0, v61, vcc
	v_add_co_u32_e32 v36, vcc, s44, v60
	global_load_dwordx4 v[32:35], v[28:29], off nt
	s_nop 0
	global_load_dwordx4 v[28:31], v[30:31], off nt
	v_addc_co_u32_e32 v37, vcc, 0, v61, vcc
	v_add_co_u32_e32 v38, vcc, s45, v60
	v_add_u32_e32 v68, 0xfffffdb0, v110
	s_nop 0
	v_addc_co_u32_e32 v39, vcc, 0, v61, vcc
	v_add_co_u32_e32 v44, vcc, s46, v60
	global_load_dwordx4 v[40:43], v[36:37], off nt
	s_nop 0
	global_load_dwordx4 v[36:39], v[38:39], off nt
	v_addc_co_u32_e32 v45, vcc, 0, v61, vcc
	v_add_co_u32_e32 v46, vcc, s47, v60
	s_movk_i32 s22, 0x80
	s_nop 0
	v_addc_co_u32_e32 v47, vcc, 0, v61, vcc
	v_add_co_u32_e32 v52, vcc, s48, v60
	global_load_dwordx4 v[48:51], v[44:45], off nt
	s_nop 0
	global_load_dwordx4 v[44:47], v[46:47], off nt
	v_addc_co_u32_e32 v53, vcc, 0, v61, vcc
	v_add_co_u32_e32 v54, vcc, 0x34000, v60
	v_mov_b32_e32 v69, s36
	s_nop 0
	v_addc_co_u32_e32 v55, vcc, 0, v61, vcc
	v_add_co_u32_e32 v62, vcc, 0x38000, v60
	global_load_dwordx4 v[56:59], v[52:53], off nt
	s_nop 0
	global_load_dwordx4 v[52:55], v[54:55], off nt
	v_addc_co_u32_e32 v63, vcc, 0, v61, vcc
	v_add_co_u32_e32 v60, vcc, 0x3c000, v60
	v_mov_b32_e32 v89, s77
	s_nop 0
	v_addc_co_u32_e32 v61, vcc, 0, v61, vcc
	global_load_dwordx4 v[64:67], v[62:63], off nt
	s_nop 0
	global_load_dwordx4 v[60:63], v[60:61], off nt
	v_cmp_gt_u32_e32 vcc, s22, v68
	v_mov_b32_e32 v68, s35
	s_nop 0
	v_cndmask_b32_e32 v69, v69, v89, vcc
	v_mov_b32_e32 v89, s76
	v_cndmask_b32_e32 v68, v68, v89, vcc
	v_cmp_ne_u64_e32 vcc, 0, v[68:69]
	s_and_saveexec_b64 s[22:23], vcc
	s_cbranch_execz .LBB0_14
	v_lshlrev_b32_e32 v88, 2, v88
	v_mov_b32_e32 v89, v2
	v_lshl_add_u64 v[88:89], v[68:69], 0, v[88:89]
	global_load_dword v68, v[88:89], off
	global_load_dword v92, v[88:89], off offset:16
	global_load_dword v112, v[88:89], off offset:32
	global_load_dword v114, v[88:89], off offset:48
	global_load_dword v116, v[88:89], off offset:64
	global_load_dword v118, v[88:89], off offset:80
	global_load_dword v120, v[88:89], off offset:96
	global_load_dword v122, v[88:89], off offset:112
	global_load_dword v124, v[88:89], off offset:128
	global_load_dword v126, v[88:89], off offset:144
	global_load_dword v128, v[88:89], off offset:160
	global_load_dword v130, v[88:89], off offset:176
	global_load_dword v132, v[88:89], off offset:192
	global_load_dword v134, v[88:89], off offset:208
	global_load_dword v136, v[88:89], off offset:224
	s_nop 0
	global_load_dword v88, v[88:89], off offset:240
	s_waitcnt vmcnt(15)
	v_pk_mul_f32 v[10:11], v[10:11], v[68:69] op_sel_hi:[1,0]
	v_pk_mul_f32 v[8:9], v[8:9], v[68:69] op_sel_hi:[1,0]
	s_waitcnt vmcnt(14)
	v_pk_mul_f32 v[6:7], v[6:7], v[92:93] op_sel_hi:[1,0]
	v_pk_mul_f32 v[4:5], v[4:5], v[92:93] op_sel_hi:[1,0]
	s_waitcnt vmcnt(13)
	v_pk_mul_f32 v[18:19], v[18:19], v[112:113] op_sel_hi:[1,0]
	v_pk_mul_f32 v[16:17], v[16:17], v[112:113] op_sel_hi:[1,0]
	s_waitcnt vmcnt(12)
	v_pk_mul_f32 v[14:15], v[14:15], v[114:115] op_sel_hi:[1,0]
	v_pk_mul_f32 v[12:13], v[12:13], v[114:115] op_sel_hi:[1,0]
	s_waitcnt vmcnt(11)
	v_pk_mul_f32 v[26:27], v[26:27], v[116:117] op_sel_hi:[1,0]
	v_pk_mul_f32 v[24:25], v[24:25], v[116:117] op_sel_hi:[1,0]
	s_waitcnt vmcnt(10)
	v_pk_mul_f32 v[22:23], v[22:23], v[118:119] op_sel_hi:[1,0]
	v_pk_mul_f32 v[20:21], v[20:21], v[118:119] op_sel_hi:[1,0]
	s_waitcnt vmcnt(9)
	v_pk_mul_f32 v[34:35], v[34:35], v[120:121] op_sel_hi:[1,0]
	v_pk_mul_f32 v[32:33], v[32:33], v[120:121] op_sel_hi:[1,0]
	s_waitcnt vmcnt(8)
	v_pk_mul_f32 v[30:31], v[30:31], v[122:123] op_sel_hi:[1,0]
	v_pk_mul_f32 v[28:29], v[28:29], v[122:123] op_sel_hi:[1,0]
	s_waitcnt vmcnt(7)
	v_pk_mul_f32 v[42:43], v[42:43], v[124:125] op_sel_hi:[1,0]
	v_pk_mul_f32 v[40:41], v[40:41], v[124:125] op_sel_hi:[1,0]
	s_waitcnt vmcnt(6)
	v_pk_mul_f32 v[38:39], v[38:39], v[126:127] op_sel_hi:[1,0]
	v_pk_mul_f32 v[36:37], v[36:37], v[126:127] op_sel_hi:[1,0]
	s_waitcnt vmcnt(5)
	v_pk_mul_f32 v[50:51], v[50:51], v[128:129] op_sel_hi:[1,0]
	v_pk_mul_f32 v[48:49], v[48:49], v[128:129] op_sel_hi:[1,0]
	s_waitcnt vmcnt(4)
	v_pk_mul_f32 v[46:47], v[46:47], v[130:131] op_sel_hi:[1,0]
	v_pk_mul_f32 v[44:45], v[44:45], v[130:131] op_sel_hi:[1,0]
	s_waitcnt vmcnt(3)
	v_pk_mul_f32 v[58:59], v[58:59], v[132:133] op_sel_hi:[1,0]
	v_pk_mul_f32 v[56:57], v[56:57], v[132:133] op_sel_hi:[1,0]
	s_waitcnt vmcnt(2)
	v_pk_mul_f32 v[54:55], v[54:55], v[134:135] op_sel_hi:[1,0]
	v_pk_mul_f32 v[52:53], v[52:53], v[134:135] op_sel_hi:[1,0]
	s_waitcnt vmcnt(1)
	v_pk_mul_f32 v[66:67], v[66:67], v[136:137] op_sel_hi:[1,0]
	v_pk_mul_f32 v[64:65], v[64:65], v[136:137] op_sel_hi:[1,0]
	s_waitcnt vmcnt(0)
	v_pk_mul_f32 v[62:63], v[62:63], v[88:89] op_sel_hi:[1,0]
	v_pk_mul_f32 v[60:61], v[60:61], v[88:89] op_sel_hi:[1,0]

; #define LAS __attribute__((address_space(3)))
; __device__ __forceinline__ void transpose_item(const float* W, int K, int N, bf16* WT, const float* gain, LAS float* scr, int item, int nblk, int lane) {
;     const int kb = item / nblk, nb = item % nblk, k0 = 64 * kb, n0 = 64 * nb;
;     const int kr = lane >> 4, nc = 4 * (lane & 15);
;     const bool ok = (n0 + nc) < N;
;     f32x4 v[16];
; #pragma unroll
;     for (int i = 0; i < 16; ++i) { v[i] = (f32x4){0.f, 0.f, 0.f, 0.f}; if (ok) v[i] = *(const f32x4*)(W + (size_t)(k0 + 4 * i + kr) * N + n0 + nc); }
;     if (gain) {
; #pragma unroll
;         for (int i = 0; i < 16; ++i) v[i] = v[i] * gain[k0 + 4 * i + kr]; }
; __device__ __forceinline__ void p0_prologue(const Args& a, LAS unsigned char* lds) {
;     ...
;         if (r < I_UKV) { transpose_item(a.w_ukv, 128, 1024, (bf16*)(ws + WS_WUKV), a.kv_a_g, scr, r, 1024 / 64, lane); continue; } r -= I_UKV;
.LBB0_15:
	s_andn2_saveexec_b64 s[22:23], s[4:5]
	s_cbranch_execz .LBB0_51
	v_add_u32_e32 v3, 0xfffffdd0, v110
	v_add_u32_e32 v4, 0xfffffdc0, v110
	v_cmp_gt_u32_e32 vcc, 16, v3
	v_mov_b32_e32 v8, v2
	v_mov_b32_e32 v9, v2
	v_cndmask_b32_e32 v4, v4, v3, vcc
	v_cmp_lt_u32_e32 vcc, 15, v3
	v_lshlrev_b32_e32 v88, 6, v4
	v_or_b32_e32 v3, v88, v95
	v_cndmask_b32_e64 v111, 0, 64, vcc
	v_or_b32_e32 v112, v111, v71
	v_ashrrev_i32_e32 v89, 31, v88
	v_mov_b32_e32 v6, v2
	v_mov_b32_e32 v7, v2
	v_mov_b64_e32 v[12:13], v[8:9]
	v_cmp_gt_i32_e64 s[4:5], s49, v3
	v_lshl_add_u64 v[90:91], v[88:89], 2, v[82:83]
	v_lshlrev_b32_e32 v92, 12, v112
	v_mov_b64_e32 v[10:11], v[6:7]
	s_and_saveexec_b64 s[30:31], s[4:5]
	s_cbranch_execz .LBB0_18
	v_mov_b32_e32 v93, v2
	v_lshl_add_u64 v[4:5], v[90:91], 0, v[92:93]
	global_load_dwordx4 v[10:13], v[4:5], off nt
.LBB0_18:
	s_or_b64 exec, exec, s[30:31]
	s_and_saveexec_b64 s[30:31], s[4:5]
	s_cbranch_execz .LBB0_20
	v_mov_b32_e32 v93, v2
	v_lshl_add_u64 v[4:5], v[90:91], 0, v[92:93]
	v_add_co_u32_e32 v4, vcc, 0x4000, v4
	s_nop 1
	v_addc_co_u32_e32 v5, vcc, 0, v5, vcc
	global_load_dwordx4 v[6:9], v[4:5], off nt
.LBB0_20:
	s_or_b64 exec, exec, s[30:31]
	v_mov_b32_e32 v4, v2
	v_mov_b32_e32 v5, v2
	v_mov_b32_e32 v3, v2
	v_mov_b64_e32 v[16:17], v[4:5]
	v_mov_b64_e32 v[14:15], v[2:3]
	s_and_saveexec_b64 s[30:31], s[4:5]
	s_cbranch_execz .LBB0_22
	v_mov_b32_e32 v93, v2
	v_lshl_add_u64 v[14:15], v[90:91], 0, v[92:93]
	v_add_co_u32_e32 v14, vcc, 0x8000, v14
	s_nop 1
	v_addc_co_u32_e32 v15, vcc, 0, v15, vcc
	global_load_dwordx4 v[14:17], v[14:15], off nt
.LBB0_22:
	s_or_b64 exec, exec, s[30:31]
	v_mov_b64_e32 v[20:21], v[4:5]
	v_mov_b64_e32 v[18:19], v[2:3]
	s_and_saveexec_b64 s[30:31], s[4:5]
	s_cbranch_execz .LBB0_24
	v_mov_b32_e32 v93, v2
	v_lshl_add_u64 v[4:5], v[90:91], 0, v[92:93]
	v_add_co_u32_e32 v4, vcc, 0xc000, v4
	s_nop 1
	v_addc_co_u32_e32 v5, vcc, 0, v5, vcc
	global_load_dwordx4 v[18:21], v[4:5], off nt
.LBB0_24:
	s_or_b64 exec, exec, s[30:31]
	v_mov_b32_e32 v4, v2
	v_mov_b32_e32 v5, v2
	v_mov_b32_e32 v3, v2
	v_mov_b64_e32 v[24:25], v[4:5]
	v_mov_b64_e32 v[22:23], v[2:3]
	s_and_saveexec_b64 s[30:31], s[4:5]
	s_cbranch_execz .LBB0_26
	v_mov_b32_e32 v93, v2
	v_lshl_add_u64 v[22:23], v[90:91], 0, v[92:93]
	v_add_co_u32_e32 v22, vcc, 0x10000, v22
	s_nop 1
	v_addc_co_u32_e32 v23, vcc, 0, v23, vcc
	global_load_dwordx4 v[22:25], v[22:23], off nt
.LBB0_26:
	s_or_b64 exec, exec, s[30:31]
	v_mov_b64_e32 v[28:29], v[4:5]
	v_mov_b64_e32 v[26:27], v[2:3]
	s_and_saveexec_b64 s[30:31], s[4:5]
	s_cbranch_execz .LBB0_28
	v_mov_b32_e32 v93, v2
	v_lshl_add_u64 v[4:5], v[90:91], 0, v[92:93]
	v_add_co_u32_e32 v4, vcc, 0x14000, v4
	s_nop 1
	v_addc_co_u32_e32 v5, vcc, 0, v5, vcc
	global_load_dwordx4 v[26:29], v[4:5], off nt
.LBB0_28:
	s_or_b64 exec, exec, s[30:31]
	v_mov_b32_e32 v4, v2
	v_mov_b32_e32 v5, v2
	v_mov_b32_e32 v3, v2
	v_mov_b64_e32 v[32:33], v[4:5]
	v_mov_b64_e32 v[30:31], v[2:3]
	s_and_saveexec_b64 s[30:31], s[4:5]
	s_cbranch_execz .LBB0_30
	v_mov_b32_e32 v93, v2
	v_lshl_add_u64 v[30:31], v[90:91], 0, v[92:93]
	v_add_co_u32_e32 v30, vcc, 0x18000, v30
	s_nop 1
	v_addc_co_u32_e32 v31, vcc, 0, v31, vcc
	global_load_dwordx4 v[30:33], v[30:31], off nt
.LBB0_30:
	s_or_b64 exec, exec, s[30:31]
	v_mov_b64_e32 v[36:37], v[4:5]
	v_mov_b64_e32 v[34:35], v[2:3]
	s_and_saveexec_b64 s[30:31], s[4:5]
	s_cbranch_execz .LBB0_32
	v_mov_b32_e32 v93, v2
	v_lshl_add_u64 v[4:5], v[90:91], 0, v[92:93]
	v_add_co_u32_e32 v4, vcc, 0x1c000, v4
	s_nop 1
	v_addc_co_u32_e32 v5, vcc, 0, v5, vcc
	global_load_dwordx4 v[34:37], v[4:5], off nt
.LBB0_32:
	s_or_b64 exec, exec, s[30:31]
	v_mov_b32_e32 v4, v2
	v_mov_b32_e32 v5, v2
	v_mov_b32_e32 v3, v2
	v_mov_b64_e32 v[40:41], v[4:5]
	v_mov_b64_e32 v[38:39], v[2:3]
	s_and_saveexec_b64 s[30:31], s[4:5]
	s_cbranch_execz .LBB0_34
	v_mov_b32_e32 v93, v2
	v_lshl_add_u64 v[38:39], v[90:91], 0, v[92:93]
	v_add_co_u32_e32 v38, vcc, 0x20000, v38
	s_nop 1
	v_addc_co_u32_e32 v39, vcc, 0, v39, vcc
	global_load_dwordx4 v[38:41], v[38:39], off nt
.LBB0_34:
	s_or_b64 exec, exec, s[30:31]
	v_mov_b64_e32 v[44:45], v[4:5]
	v_mov_b64_e32 v[42:43], v[2:3]
	s_and_saveexec_b64 s[30:31], s[4:5]
	s_cbranch_execz .LBB0_36
	v_mov_b32_e32 v93, v2
	v_lshl_add_u64 v[4:5], v[90:91], 0, v[92:93]
	v_add_co_u32_e32 v4, vcc, 0x24000, v4
	s_nop 1
	v_addc_co_u32_e32 v5, vcc, 0, v5, vcc
	global_load_dwordx4 v[42:45], v[4:5], off nt
.LBB0_36:
	s_or_b64 exec, exec, s[30:31]
	v_mov_b32_e32 v4, v2
	v_mov_b32_e32 v5, v2
	v_mov_b32_e32 v3, v2
	v_mov_b64_e32 v[48:49], v[4:5]
	v_mov_b64_e32 v[46:47], v[2:3]
	s_and_saveexec_b64 s[30:31], s[4:5]
	s_cbranch_execz .LBB0_38
	v_mov_b32_e32 v93, v2
	v_lshl_add_u64 v[46:47], v[90:91], 0, v[92:93]
	v_add_co_u32_e32 v46, vcc, 0x28000, v46
	s_nop 1
	v_addc_co_u32_e32 v47, vcc, 0, v47, vcc
	global_load_dwordx4 v[46:49], v[46:47], off nt
.LBB0_38:
	s_or_b64 exec, exec, s[30:31]
	v_mov_b64_e32 v[52:53], v[4:5]
	v_mov_b64_e32 v[50:51], v[2:3]
	s_and_saveexec_b64 s[30:31], s[4:5]
	s_cbranch_execz .LBB0_40
	v_mov_b32_e32 v93, v2
	v_lshl_add_u64 v[4:5], v[90:91], 0, v[92:93]
	v_add_co_u32_e32 v4, vcc, 0x2c000, v4
	s_nop 1
	v_addc_co_u32_e32 v5, vcc, 0, v5, vcc
	global_load_dwordx4 v[50:53], v[4:5], off nt
.LBB0_40:
	s_or_b64 exec, exec, s[30:31]
	v_mov_b32_e32 v4, v2
	v_mov_b32_e32 v5, v2
	v_mov_b32_e32 v3, v2
	v_mov_b64_e32 v[56:57], v[4:5]
	v_mov_b64_e32 v[54:55], v[2:3]
	s_and_saveexec_b64 s[30:31], s[4:5]
	s_cbranch_execz .LBB0_42
	v_mov_b32_e32 v93, v2
	v_lshl_add_u64 v[54:55], v[90:91], 0, v[92:93]
	v_add_co_u32_e32 v54, vcc, 0x30000, v54
	s_nop 1
	v_addc_co_u32_e32 v55, vcc, 0, v55, vcc
	global_load_dwordx4 v[54:57], v[54:55], off nt
.LBB0_42:
	s_or_b64 exec, exec, s[30:31]
	v_mov_b64_e32 v[60:61], v[4:5]
	v_mov_b64_e32 v[58:59], v[2:3]
	s_and_saveexec_b64 s[30:31], s[4:5]
	s_cbranch_execz .LBB0_44
	v_mov_b32_e32 v93, v2
	v_lshl_add_u64 v[4:5], v[90:91], 0, v[92:93]
	v_add_co_u32_e32 v4, vcc, 0x34000, v4
	s_nop 1
	v_addc_co_u32_e32 v5, vcc, 0, v5, vcc
	global_load_dwordx4 v[58:61], v[4:5], off nt
.LBB0_44:
	s_or_b64 exec, exec, s[30:31]
	v_mov_b32_e32 v4, v2
	v_mov_b32_e32 v5, v2
	v_mov_b32_e32 v3, v2
	v_mov_b64_e32 v[64:65], v[4:5]
	v_mov_b64_e32 v[62:63], v[2:3]
	s_and_saveexec_b64 s[30:31], s[4:5]
	s_cbranch_execz .LBB0_46
	v_mov_b32_e32 v93, v2
	v_lshl_add_u64 v[62:63], v[90:91], 0, v[92:93]
	v_add_co_u32_e32 v62, vcc, 0x38000, v62
	s_nop 1
	v_addc_co_u32_e32 v63, vcc, 0, v63, vcc
	global_load_dwordx4 v[62:65], v[62:63], off nt
.LBB0_46:
	s_or_b64 exec, exec, s[30:31]
	v_mov_b64_e32 v[68:69], v[4:5]
	v_mov_b64_e32 v[66:67], v[2:3]
	s_and_saveexec_b64 s[30:31], s[4:5]
	s_cbranch_execz .LBB0_48
	v_mov_b32_e32 v93, v2
	v_lshl_add_u64 v[4:5], v[90:91], 0, v[92:93]
	v_add_co_u32_e32 v4, vcc, 0x3c000, v4
	s_nop 1
	v_addc_co_u32_e32 v5, vcc, 0, v5, vcc
	global_load_dwordx4 v[66:69], v[4:5], off nt

; #define LAS __attribute__((address_space(3)))
; __device__ __forceinline__ void transpose_item(const float* W, int K, int N, bf16* WT, const float* gain, LAS float* scr, int item, int nblk, int lane) {
;     const int kb = item / nblk, nb = item % nblk, k0 = 64 * kb, n0 = 64 * nb;
;     const int kr = lane >> 4, nc = 4 * (lane & 15);
;     const bool ok = (n0 + nc) < N;
;     f32x4 v[16];
; #pragma unroll
;     for (int i = 0; i < 16; ++i) { v[i] = (f32x4){0.f, 0.f, 0.f, 0.f}; if (ok) v[i] = *(const f32x4*)(W + (size_t)(k0 + 4 * i + kr) * N + n0 + nc); }
;     if (gain) {
; #pragma unroll
;         for (int i = 0; i < 16; ++i) v[i] = v[i] * gain[k0 + 4 * i + kr]; }
; __device__ __forceinline__ void p0_prologue(const Args& a, LAS unsigned char* lds) {
;     ...
;         if (r < I_UQ) { transpose_item(a.w_uq, 256, 768, (bf16*)(ws + WS_WUQ), a.q_a_g, scr, r, 768 / 64, lane); continue; } r -= I_UQ;
.LBB0_52:
	s_andn2_saveexec_b64 s[4:5], s[18:19]
	s_cbranch_execz .LBB0_56
	v_mul_lo_u16_sdwa v3, v110, s50 dst_sel:DWORD dst_unused:UNUSED_PAD src0_sel:BYTE_0 src1_sel:DWORD
	v_lshrrev_b16_e32 v3, 11, v3
	v_mul_lo_u16_e32 v4, 12, v3
	v_lshlrev_b32_e32 v3, 6, v3
	v_sub_u16_e32 v68, v110, v4
	v_or_b32_e32 v69, v3, v71
	v_lshlrev_b32_sdwa v4, v108, v68 dst_sel:DWORD dst_unused:UNUSED_PAD src0_sel:DWORD src1_sel:BYTE_0
	v_mov_b32_e32 v5, v2
	v_mul_u32_u24_e32 v6, 0x300, v69
	v_lshl_add_u64 v[4:5], v[84:85], 0, v[4:5]
	v_lshlrev_b32_e32 v6, 2, v6
	v_mov_b32_e32 v7, v2
	v_lshl_add_u64 v[60:61], v[4:5], 0, v[6:7]
	v_add_co_u32_e32 v4, vcc, s51, v60
	s_nop 1
	v_addc_co_u32_e32 v5, vcc, 0, v61, vcc
	v_add_co_u32_e32 v12, vcc, s52, v60
	global_load_dwordx4 v[8:11], v[60:61], off nt
	s_nop 0
	global_load_dwordx4 v[4:7], v[4:5], off nt
	v_addc_co_u32_e32 v13, vcc, 0, v61, vcc
	v_add_co_u32_e32 v14, vcc, s53, v60
	s_nop 1
	v_addc_co_u32_e32 v15, vcc, 0, v61, vcc
	v_add_co_u32_e32 v20, vcc, s41, v60
	global_load_dwordx4 v[16:19], v[12:13], off nt
	s_nop 0
	global_load_dwordx4 v[12:15], v[14:15], off nt
	v_addc_co_u32_e32 v21, vcc, 0, v61, vcc
	v_add_co_u32_e32 v22, vcc, s54, v60
	s_nop 1
	v_addc_co_u32_e32 v23, vcc, 0, v61, vcc
	v_add_co_u32_e32 v28, vcc, s55, v60
	global_load_dwordx4 v[24:27], v[20:21], off nt
	s_nop 0
	global_load_dwordx4 v[20:23], v[22:23], off nt
	v_addc_co_u32_e32 v29, vcc, 0, v61, vcc
	v_add_co_u32_e32 v30, vcc, s56, v60
	s_nop 1
	v_addc_co_u32_e32 v31, vcc, 0, v61, vcc
	v_add_co_u32_e32 v36, vcc, s43, v60
	global_load_dwordx4 v[32:35], v[28:29], off nt
	s_nop 0
	global_load_dwordx4 v[28:31], v[30:31], off nt
	v_addc_co_u32_e32 v37, vcc, 0, v61, vcc
	v_add_co_u32_e32 v38, vcc, s57, v60
	s_nop 1
	v_addc_co_u32_e32 v39, vcc, 0, v61, vcc
	v_add_co_u32_e32 v44, vcc, s58, v60
	global_load_dwordx4 v[40:43], v[36:37], off nt
	s_nop 0
	global_load_dwordx4 v[36:39], v[38:39], off nt
	v_addc_co_u32_e32 v45, vcc, 0, v61, vcc
	v_add_co_u32_e32 v46, vcc, s59, v60
	s_nop 1
	v_addc_co_u32_e32 v47, vcc, 0, v61, vcc
	v_add_co_u32_e32 v52, vcc, s45, v60
	global_load_dwordx4 v[48:51], v[44:45], off nt
	s_nop 0
	global_load_dwordx4 v[44:47], v[46:47], off nt
	v_addc_co_u32_e32 v53, vcc, 0, v61, vcc
	v_add_co_u32_e32 v54, vcc, 0x27000, v60
	s_nop 1
	v_addc_co_u32_e32 v55, vcc, 0, v61, vcc
	v_add_co_u32_e32 v62, vcc, 0x2a000, v60
	global_load_dwordx4 v[56:59], v[52:53], off nt
	s_nop 0
	global_load_dwordx4 v[52:55], v[54:55], off nt
	v_addc_co_u32_e32 v63, vcc, 0, v61, vcc
	v_add_co_u32_e32 v60, vcc, 0x2d000, v60
	s_nop 1
	v_addc_co_u32_e32 v61, vcc, 0, v61, vcc
	global_load_dwordx4 v[64:67], v[62:63], off nt
	s_nop 0
	global_load_dwordx4 v[60:63], v[60:61], off nt
	s_andn2_b64 vcc, exec, s[28:29]
	s_cbranch_vccnz .LBB0_55
	v_lshlrev_b32_e32 v69, 2, v69
	global_load_dword v88, v69, s[16:17]
	global_load_dword v90, v69, s[16:17] offset:16
	global_load_dword v92, v69, s[16:17] offset:32
	global_load_dword v112, v69, s[16:17] offset:48
	global_load_dword v114, v69, s[16:17] offset:64
	global_load_dword v116, v69, s[16:17] offset:80
	global_load_dword v118, v69, s[16:17] offset:96
	global_load_dword v120, v69, s[16:17] offset:112
	global_load_dword v122, v69, s[16:17] offset:128
	global_load_dword v124, v69, s[16:17] offset:144
	global_load_dword v126, v69, s[16:17] offset:160
	global_load_dword v128, v69, s[16:17] offset:176
	global_load_dword v130, v69, s[16:17] offset:192
	global_load_dword v132, v69, s[16:17] offset:208
	global_load_dword v134, v69, s[16:17] offset:224
	global_load_dword v136, v69, s[16:17] offset:240
	s_waitcnt vmcnt(15)
	v_pk_mul_f32 v[10:11], v[10:11], v[88:89] op_sel_hi:[1,0]
	v_pk_mul_f32 v[8:9], v[8:9], v[88:89] op_sel_hi:[1,0]
	s_waitcnt vmcnt(14)
	v_pk_mul_f32 v[6:7], v[6:7], v[90:91] op_sel_hi:[1,0]
	v_pk_mul_f32 v[4:5], v[4:5], v[90:91] op_sel_hi:[1,0]
	s_waitcnt vmcnt(13)
	v_pk_mul_f32 v[18:19], v[18:19], v[92:93] op_sel_hi:[1,0]
	v_pk_mul_f32 v[16:17], v[16:17], v[92:93] op_sel_hi:[1,0]
	s_waitcnt vmcnt(12)
	v_pk_mul_f32 v[14:15], v[14:15], v[112:113] op_sel_hi:[1,0]
	v_pk_mul_f32 v[12:13], v[12:13], v[112:113] op_sel_hi:[1,0]
	s_waitcnt vmcnt(11)
	v_pk_mul_f32 v[26:27], v[26:27], v[114:115] op_sel_hi:[1,0]
	v_pk_mul_f32 v[24:25], v[24:25], v[114:115] op_sel_hi:[1,0]
	s_waitcnt vmcnt(10)
	v_pk_mul_f32 v[22:23], v[22:23], v[116:117] op_sel_hi:[1,0]
	v_pk_mul_f32 v[20:21], v[20:21], v[116:117] op_sel_hi:[1,0]
	s_waitcnt vmcnt(9)
	v_pk_mul_f32 v[34:35], v[34:35], v[118:119] op_sel_hi:[1,0]
	v_pk_mul_f32 v[32:33], v[32:33], v[118:119] op_sel_hi:[1,0]
	s_waitcnt vmcnt(8)
	v_pk_mul_f32 v[30:31], v[30:31], v[120:121] op_sel_hi:[1,0]
	v_pk_mul_f32 v[28:29], v[28:29], v[120:121] op_sel_hi:[1,0]
	s_waitcnt vmcnt(7)
	v_pk_mul_f32 v[42:43], v[42:43], v[122:123] op_sel_hi:[1,0]
	v_pk_mul_f32 v[40:41], v[40:41], v[122:123] op_sel_hi:[1,0]
	s_waitcnt vmcnt(6)
	v_pk_mul_f32 v[38:39], v[38:39], v[124:125] op_sel_hi:[1,0]
	v_pk_mul_f32 v[36:37], v[36:37], v[124:125] op_sel_hi:[1,0]
	s_waitcnt vmcnt(5)
	v_pk_mul_f32 v[50:51], v[50:51], v[126:127] op_sel_hi:[1,0]
	v_pk_mul_f32 v[48:49], v[48:49], v[126:127] op_sel_hi:[1,0]
	s_waitcnt vmcnt(4)
	v_pk_mul_f32 v[46:47], v[46:47], v[128:129] op_sel_hi:[1,0]
	v_pk_mul_f32 v[44:45], v[44:45], v[128:129] op_sel_hi:[1,0]
	s_waitcnt vmcnt(3)
	v_pk_mul_f32 v[58:59], v[58:59], v[130:131] op_sel_hi:[1,0]
	v_pk_mul_f32 v[56:57], v[56:57], v[130:131] op_sel_hi:[1,0]
	s_waitcnt vmcnt(2)
	v_pk_mul_f32 v[54:55], v[54:55], v[132:133] op_sel_hi:[1,0]
	v_pk_mul_f32 v[52:53], v[52:53], v[132:133] op_sel_hi:[1,0]
	s_waitcnt vmcnt(1)
	v_pk_mul_f32 v[66:67], v[66:67], v[134:135] op_sel_hi:[1,0]
	v_pk_mul_f32 v[64:65], v[64:65], v[134:135] op_sel_hi:[1,0]
	s_waitcnt vmcnt(0)
	v_pk_mul_f32 v[62:63], v[62:63], v[136:137] op_sel_hi:[1,0]
	v_pk_mul_f32 v[60:61], v[60:61], v[136:137] op_sel_hi:[1,0]

; #define LAS __attribute__((address_space(3)))
; __device__ __forceinline__ void transpose_item(const float* W, int K, int N, bf16* WT, const float* gain, LAS float* scr, int item, int nblk, int lane) {
;     const int kb = item / nblk, nb = item % nblk, k0 = 64 * kb, n0 = 64 * nb;
;     const int kr = lane >> 4, nc = 4 * (lane & 15);
;     const bool ok = (n0 + nc) < N;
;     f32x4 v[16];
; #pragma unroll
;     for (int i = 0; i < 16; ++i) { v[i] = (f32x4){0.f, 0.f, 0.f, 0.f}; if (ok) v[i] = *(const f32x4*)(W + (size_t)(k0 + 4 * i + kr) * N + n0 + nc); }
; __device__ __forceinline__ void p0_prologue(const Args& a, LAS unsigned char* lds) {
;     ...
;         if (r < I_IN) { transpose_item(a.w_in, D_, INW, (bf16*)(ws + WS_WIN), nullptr, scr, r, NPROJ / 64, lane); continue; } r -= I_IN;
.LBB0_57:
	s_andn2_saveexec_b64 s[4:5], s[14:15]
	s_cbranch_execz .LBB0_8
	v_ashrrev_i32_e32 v3, 31, v110
	v_lshrrev_b32_e32 v3, 27, v3
	v_add_u32_e32 v3, v110, v3
	v_ashrrev_i32_e32 v3, 5, v3
	v_lshlrev_b32_e32 v68, 6, v3
	v_lshlrev_b32_e32 v3, 11, v3
	v_sub_u32_e32 v4, v106, v3
	v_add_u32_e32 v5, v4, v95
	v_cmp_gt_i32_e32 vcc, s60, v5
	v_ashrrev_i32_e32 v5, 31, v4
	v_or_b32_e32 v69, v68, v71
	v_lshl_add_u64 v[88:89], v[4:5], 2, v[86:87]
	v_mov_b32_e32 v4, 0
	v_mov_b32_e32 v8, 0
	v_mov_b32_e32 v9, 0
	v_mov_b32_e32 v10, 0
	v_mov_b32_e32 v11, 0
	s_and_saveexec_b64 s[14:15], vcc
	s_cbranch_execz .LBB0_60
	v_mad_i64_i32 v[6:7], s[18:19], v69, s61, v[88:89]
	global_load_dwordx4 v[8:11], v[6:7], off nt
.LBB0_60:
	s_or_b64 exec, exec, s[14:15]
	v_mov_b32_e32 v5, 0
	v_mov_b32_e32 v6, 0
	v_mov_b32_e32 v7, 0
	s_and_saveexec_b64 s[14:15], vcc
	s_cbranch_execz .LBB0_62
	v_or_b32_e32 v4, 4, v69
	v_mad_i64_i32 v[4:5], s[18:19], v4, s61, v[88:89]
	global_load_dwordx4 v[4:7], v[4:5], off nt
.LBB0_62:
	s_or_b64 exec, exec, s[14:15]
	v_mov_b32_e32 v12, 0
	v_mov_b32_e32 v16, 0
	v_mov_b32_e32 v17, 0
	v_mov_b32_e32 v18, 0
	v_mov_b32_e32 v19, 0
	s_and_saveexec_b64 s[14:15], vcc
	s_cbranch_execz .LBB0_64
	v_or_b32_e32 v13, 8, v69
	v_mad_i64_i32 v[14:15], s[18:19], v13, s61, v[88:89]
	global_load_dwordx4 v[16:19], v[14:15], off nt
.LBB0_64:
	s_or_b64 exec, exec, s[14:15]
	v_mov_b32_e32 v13, 0
	v_mov_b32_e32 v14, 0
	v_mov_b32_e32 v15, 0
	s_and_saveexec_b64 s[14:15], vcc
	s_cbranch_execz .LBB0_66
	v_or_b32_e32 v12, 12, v69
	v_mad_i64_i32 v[12:13], s[18:19], v12, s61, v[88:89]
	global_load_dwordx4 v[12:15], v[12:13], off nt
.LBB0_66:
	s_or_b64 exec, exec, s[14:15]
	v_mov_b32_e32 v20, 0
	v_mov_b32_e32 v24, 0
	v_mov_b32_e32 v25, 0
	v_mov_b32_e32 v26, 0
	v_mov_b32_e32 v27, 0
	s_and_saveexec_b64 s[14:15], vcc
	s_cbranch_execz .LBB0_68
	v_or_b32_e32 v21, 16, v69
	v_mad_i64_i32 v[22:23], s[18:19], v21, s61, v[88:89]
	global_load_dwordx4 v[24:27], v[22:23], off nt
.LBB0_68:
	s_or_b64 exec, exec, s[14:15]
	v_mov_b32_e32 v21, 0
	v_mov_b32_e32 v22, 0
	v_mov_b32_e32 v23, 0
	s_and_saveexec_b64 s[14:15], vcc
	s_cbranch_execz .LBB0_70
	v_or_b32_e32 v20, 20, v69
	v_mad_i64_i32 v[20:21], s[18:19], v20, s61, v[88:89]
	global_load_dwordx4 v[20:23], v[20:21], off nt
.LBB0_70:
	s_or_b64 exec, exec, s[14:15]
	v_mov_b32_e32 v28, 0
	v_mov_b32_e32 v32, 0
	v_mov_b32_e32 v33, 0
	v_mov_b32_e32 v34, 0
	v_mov_b32_e32 v35, 0
	s_and_saveexec_b64 s[14:15], vcc
	s_cbranch_execz .LBB0_72
	v_or_b32_e32 v29, 24, v69
	v_mad_i64_i32 v[30:31], s[18:19], v29, s61, v[88:89]
	global_load_dwordx4 v[32:35], v[30:31], off nt
.LBB0_72:
	s_or_b64 exec, exec, s[14:15]
	v_mov_b32_e32 v29, 0
	v_mov_b32_e32 v30, 0
	v_mov_b32_e32 v31, 0
	s_and_saveexec_b64 s[14:15], vcc
	s_cbranch_execz .LBB0_74
	v_or_b32_e32 v28, 28, v69
	v_mad_i64_i32 v[28:29], s[18:19], v28, s61, v[88:89]
	global_load_dwordx4 v[28:31], v[28:29], off nt
.LBB0_74:
	s_or_b64 exec, exec, s[14:15]
	v_mov_b32_e32 v36, 0
	v_mov_b32_e32 v40, 0
	v_mov_b32_e32 v41, 0
	v_mov_b32_e32 v42, 0
	v_mov_b32_e32 v43, 0
	s_and_saveexec_b64 s[14:15], vcc
	s_cbranch_execz .LBB0_76
	v_or_b32_e32 v37, 32, v69
	v_mad_i64_i32 v[38:39], s[18:19], v37, s61, v[88:89]
	global_load_dwordx4 v[40:43], v[38:39], off nt
.LBB0_76:
	s_or_b64 exec, exec, s[14:15]
	v_mov_b32_e32 v37, 0
	v_mov_b32_e32 v38, 0
	v_mov_b32_e32 v39, 0
	s_and_saveexec_b64 s[14:15], vcc
	s_cbranch_execz .LBB0_78
	v_or_b32_e32 v36, 36, v69
	v_mad_i64_i32 v[36:37], s[18:19], v36, s61, v[88:89]
	global_load_dwordx4 v[36:39], v[36:37], off nt
.LBB0_78:
	s_or_b64 exec, exec, s[14:15]
	v_mov_b32_e32 v44, 0
	v_mov_b32_e32 v48, 0
	v_mov_b32_e32 v49, 0
	v_mov_b32_e32 v50, 0
	v_mov_b32_e32 v51, 0
	s_and_saveexec_b64 s[14:15], vcc
	s_cbranch_execz .LBB0_80
	v_or_b32_e32 v45, 40, v69
	v_mad_i64_i32 v[46:47], s[18:19], v45, s61, v[88:89]
	global_load_dwordx4 v[48:51], v[46:47], off nt
.LBB0_80:
	s_or_b64 exec, exec, s[14:15]
	v_mov_b32_e32 v45, 0
	v_mov_b32_e32 v46, 0
	v_mov_b32_e32 v47, 0
	s_and_saveexec_b64 s[14:15], vcc
	s_cbranch_execz .LBB0_82
	v_or_b32_e32 v44, 44, v69
	v_mad_i64_i32 v[44:45], s[18:19], v44, s61, v[88:89]
	global_load_dwordx4 v[44:47], v[44:45], off nt
.LBB0_82:
	s_or_b64 exec, exec, s[14:15]
	v_mov_b32_e32 v52, 0
	v_mov_b32_e32 v56, 0
	v_mov_b32_e32 v57, 0
	v_mov_b32_e32 v58, 0
	v_mov_b32_e32 v59, 0
	s_and_saveexec_b64 s[14:15], vcc
	s_cbranch_execz .LBB0_84
	v_or_b32_e32 v53, 48, v69
	v_mad_i64_i32 v[54:55], s[18:19], v53, s61, v[88:89]
	global_load_dwordx4 v[56:59], v[54:55], off nt
.LBB0_84:
	s_or_b64 exec, exec, s[14:15]
	v_mov_b32_e32 v53, 0
	v_mov_b32_e32 v54, 0
	v_mov_b32_e32 v55, 0
	s_and_saveexec_b64 s[14:15], vcc
	s_cbranch_execz .LBB0_86
	v_or_b32_e32 v52, 52, v69
	v_mad_i64_i32 v[52:53], s[18:19], v52, s61, v[88:89]
	global_load_dwordx4 v[52:55], v[52:53], off nt
.LBB0_86:
	s_or_b64 exec, exec, s[14:15]
	v_mov_b32_e32 v60, 0
	v_mov_b32_e32 v64, 0
	v_mov_b32_e32 v65, 0
	v_mov_b32_e32 v66, 0
	v_mov_b32_e32 v67, 0
	s_and_saveexec_b64 s[14:15], vcc
	s_cbranch_execz .LBB0_88
	v_or_b32_e32 v61, 56, v69
	v_mad_i64_i32 v[62:63], s[18:19], v61, s61, v[88:89]
	global_load_dwordx4 v[64:67], v[62:63], off nt
.LBB0_88:
	s_or_b64 exec, exec, s[14:15]
	v_mov_b32_e32 v61, 0
	v_mov_b32_e32 v62, 0
	v_mov_b32_e32 v63, 0
	s_and_saveexec_b64 s[14:15], vcc
	s_cbranch_execz .LBB0_7
	v_or_b32_e32 v60, 60, v69
	v_mad_i64_i32 v[60:61], s[18:19], v60, s61, v[88:89]
	global_load_dwordx4 v[60:63], v[60:61], off nt
	s_branch .LBB0_7

; __device__ __forceinline__ unsigned pk2(float lo, float hi) { f32x2 v = {lo, hi}; bf16x2_t b = __builtin_convertvector(v, bf16x2_t); return __builtin_bit_cast(unsigned, b); }
; __device__ __forceinline__ void rms_row_to_bf16(const float* xrow, const float* g, bf16* orow, int lane) {
;     const f32x4* xr = (const f32x4*)xrow + lane; const f32x4* gr = (const f32x4*)g + lane;
;     f32x4 v[4]; float s = 0.f;
; #pragma unroll
;     for (int j = 0; j < 4; ++j) { v[j] = xr[64 * j]; s += (v[j].x * v[j].x + v[j].y * v[j].y) + (v[j].z * v[j].z + v[j].w * v[j].w); }
;     const float rstd = 1.f / sqrtf(wave_sum(s) * (1.f / D_) + EPS);
;     u32x2* o8 = (u32x2*)orow + lane;
; #pragma unroll
;     for (int j = 0; j < 4; ++j) { const f32x4 gg = gr[64 * j]; u32x2 o; o.x = pk2(v[j].x * rstd * gg.x, v[j].y * rstd * gg.y); o.y = pk2(v[j].z * rstd * gg.z, v[j].w * rstd * gg.w); o8[64 * j] = o; }
; __device__ __forceinline__ void p0_prologue(const Args& a, LAS unsigned char* lds) {
;     ...
;     for (int m = gw; m < T_; m += NGW) rms_row_to_bf16(a.x + (size_t)m * D_, a.ln_mix_g, H + (size_t)m * D_, lane);
.LBB0_92:
	v_readfirstlane_b32 s98, v70
	s_nop 3
	s_mov_b32 s100, 0
	global_load_dwordx4 v[32:35], v[2:3], off
	global_load_dwordx4 v[72:75], v[2:3], off offset:1024
	global_load_dwordx4 v[76:79], v[2:3], off offset:2048
	global_load_dwordx4 v[80:83], v[2:3], off offset:3072
	global_load_dwordx4 v[16:19], v[6:7], off offset:-3072 nt
	global_load_dwordx4 v[20:23], v[6:7], off offset:-2048 nt
	global_load_dwordx4 v[24:27], v[6:7], off offset:-1024 nt
	global_load_dwordx4 v[28:31], v[6:7], off nt
.Lrms_loop:
	s_add_i32 s99, s98, s40
	s_cmp_lt_i32 s99, 0x4000
	s_cbranch_scc0 .Lrms_np_a
	v_lshl_add_u64 v[6:7], v[6:7], 0, s[14:15]
	global_load_dwordx4 v[84:87], v[6:7], off offset:-3072 nt
	global_load_dwordx4 v[88:91], v[6:7], off offset:-2048 nt
	global_load_dwordx4 v[92:95], v[6:7], off offset:-1024 nt
	global_load_dwordx4 v[96:99], v[6:7], off nt
	s_cmp_eq_u32 s100, 0
	s_cbranch_scc1 .Lrms_w4_a
	s_waitcnt vmcnt(8)
	s_branch .Lrms_go_a

; __device__ __forceinline__ unsigned pk2(float lo, float hi) { f32x2 v = {lo, hi}; bf16x2_t b = __builtin_convertvector(v, bf16x2_t); return __builtin_bit_cast(unsigned, b); }
; __device__ __forceinline__ void rms_row_to_bf16(const float* xrow, const float* g, bf16* orow, int lane) {
;     const f32x4* xr = (const f32x4*)xrow + lane; const f32x4* gr = (const f32x4*)g + lane;
;     f32x4 v[4]; float s = 0.f;
; #pragma unroll
;     for (int j = 0; j < 4; ++j) { v[j] = xr[64 * j]; s += (v[j].x * v[j].x + v[j].y * v[j].y) + (v[j].z * v[j].z + v[j].w * v[j].w); }
;     const float rstd = 1.f / sqrtf(wave_sum(s) * (1.f / D_) + EPS);
;     u32x2* o8 = (u32x2*)orow + lane;
; #pragma unroll
;     for (int j = 0; j < 4; ++j) { const f32x4 gg = gr[64 * j]; u32x2 o; o.x = pk2(v[j].x * rstd * gg.x, v[j].y * rstd * gg.y); o.y = pk2(v[j].z * rstd * gg.z, v[j].w * rstd * gg.w); o8[64 * j] = o; }
.Lrms_go_a:
	v_pk_mul_f32 v[36:37], v[18:19], v[18:19]
	v_pk_mul_f32 v[38:39], v[16:17], v[16:17]
	v_pk_mul_f32 v[40:41], v[22:23], v[22:23]
	v_pk_mul_f32 v[42:43], v[20:21], v[20:21]
	v_pk_mov_b32 v[48:49], v[38:39], v[36:37] op_sel:[1,0]
	v_mov_b32_e32 v39, v37
	v_pk_mov_b32 v[36:37], v[42:43], v[40:41] op_sel:[1,0]
	v_mov_b32_e32 v43, v41
	v_mul_f32_e32 v47, v28, v28
	v_mul_f32_e32 v44, v25, v25
	v_mul_f32_e32 v46, v27, v27
	v_pk_add_f32 v[38:39], v[48:49], v[38:39]
	v_pk_add_f32 v[36:37], v[36:37], v[42:43]
	v_mul_f32_e32 v50, v29, v29
	v_mul_f32_e32 v51, v30, v30
	v_mul_f32_e32 v52, v31, v31
	v_pk_fma_f32 v[40:41], v[24:25], v[24:25], v[44:45] op_sel_hi:[1,1,0]
	v_pk_fma_f32 v[44:45], v[26:27], v[26:27], v[46:47] op_sel_hi:[1,1,0]
	v_pk_add_f32 v[38:39], v[38:39], v[38:39] op_sel:[0,1] op_sel_hi:[1,0]
	v_pk_add_f32 v[36:37], v[36:37], v[36:37] op_sel:[0,1] op_sel_hi:[1,0]
	v_mov_b32_e32 v41, v51
	v_mov_b32_e32 v45, v52
	v_mov_b32_e32 v39, v47
	v_mov_b32_e32 v37, v50
	v_pk_add_f32 v[40:41], v[40:41], v[44:45]
	v_pk_add_f32 v[36:37], v[38:39], v[36:37]
	s_nop 0
	v_pk_add_f32 v[36:37], v[36:37], v[40:41]
	s_nop 0
	v_add_f32_e32 v36, v36, v37
	ds_bpermute_b32 v37, v8, v36
	s_waitcnt lgkmcnt(0)
	v_add_f32_e32 v36, v36, v37
	ds_bpermute_b32 v37, v9, v36
	s_waitcnt lgkmcnt(0)
	v_add_f32_e32 v36, v36, v37
	ds_bpermute_b32 v37, v10, v36
	s_waitcnt lgkmcnt(0)
	v_add_f32_e32 v36, v36, v37
	ds_bpermute_b32 v37, v11, v36
	s_waitcnt lgkmcnt(0)
	v_add_f32_e32 v36, v36, v37
	ds_bpermute_b32 v37, v12, v36
	s_waitcnt lgkmcnt(0)
	v_add_f32_e32 v36, v36, v37
	ds_bpermute_b32 v37, v13, v36
	s_waitcnt lgkmcnt(0)
	v_add_f32_e32 v36, v36, v37
	v_fmamk_f32 v36, v36, 0x3a800000, v14
	v_mul_f32_e32 v37, 0x4f800000, v36
	v_cmp_gt_f32_e32 vcc, s18, v36
	s_nop 1
	v_cndmask_b32_e32 v36, v36, v37, vcc
	v_sqrt_f32_e32 v37, v36
	s_nop 0
	v_add_u32_e32 v38, -1, v37
	v_add_u32_e32 v39, 1, v37
	v_fma_f32 v40, -v38, v37, v36
	v_fma_f32 v41, -v39, v37, v36
	v_cmp_ge_f32_e64 s[0:1], 0, v40
	s_nop 1
	v_cndmask_b32_e64 v37, v37, v38, s[0:1]
	v_cmp_lt_f32_e64 s[0:1], 0, v41
	s_nop 1
	v_cndmask_b32_e64 v37, v37, v39, s[0:1]
	v_mul_f32_e32 v38, 0x37800000, v37
	v_cndmask_b32_e32 v37, v37, v38, vcc
	v_cmp_class_f32_e32 vcc, v36, v15
	s_nop 1
	v_cndmask_b32_e32 v36, v37, v36, vcc
	v_div_scale_f32 v37, s[0:1], v36, v36, 1.0
	v_rcp_f32_e32 v39, v37
	v_div_scale_f32 v38, vcc, 1.0, v36, 1.0
	v_fma_f32 v40, -v37, v39, 1.0
	v_fmac_f32_e32 v39, v40, v39
	v_mul_f32_e32 v40, v38, v39
	v_fma_f32 v41, -v37, v40, v38
	v_fmac_f32_e32 v40, v41, v39
	v_fma_f32 v37, -v37, v40, v38
	v_div_fmas_f32 v37, v37, v39, v40
	v_div_fixup_f32 v36, v37, v36, 1.0
	v_pk_mul_f32 v[16:17], v[16:17], v[36:37] op_sel_hi:[1,0]
	v_pk_mul_f32 v[18:19], v[18:19], v[36:37] op_sel_hi:[1,0]
	v_pk_mul_f32 v[20:21], v[20:21], v[36:37] op_sel_hi:[1,0]
	v_pk_mul_f32 v[22:23], v[22:23], v[36:37] op_sel_hi:[1,0]
	v_pk_mul_f32 v[24:25], v[24:25], v[36:37] op_sel_hi:[1,0]
	v_pk_mul_f32 v[26:27], v[26:27], v[36:37] op_sel_hi:[1,0]
	v_pk_mul_f32 v[28:29], v[28:29], v[36:37] op_sel_hi:[1,0]
	v_pk_mul_f32 v[30:31], v[30:31], v[36:37] op_sel_hi:[1,0]
	v_pk_mul_f32 v[16:17], v[32:33], v[16:17]
	v_pk_mul_f32 v[18:19], v[34:35], v[18:19]
	v_pk_mul_f32 v[20:21], v[72:73], v[20:21]
	v_pk_mul_f32 v[22:23], v[74:75], v[22:23]
	v_pk_mul_f32 v[24:25], v[76:77], v[24:25]
	v_pk_mul_f32 v[26:27], v[78:79], v[26:27]
	v_pk_mul_f32 v[28:29], v[80:81], v[28:29]
	v_pk_mul_f32 v[30:31], v[82:83], v[30:31]
	v_cvt_pk_bf16_f32 v100, v16, v17
	v_cvt_pk_bf16_f32 v101, v18, v19
	v_cvt_pk_bf16_f32 v102, v20, v21
	v_cvt_pk_bf16_f32 v103, v22, v23
	v_cvt_pk_bf16_f32 v104, v24, v25
	v_cvt_pk_bf16_f32 v105, v26, v27
	v_cvt_pk_bf16_f32 v106, v28, v29
	v_cvt_pk_bf16_f32 v107, v30, v31
	global_store_dwordx2 v[4:5], v[100:101], off
	global_store_dwordx2 v[4:5], v[102:103], off offset:512
	global_store_dwordx2 v[4:5], v[104:105], off offset:1024
	global_store_dwordx2 v[4:5], v[106:107], off offset:1536
	v_lshl_add_u64 v[4:5], v[4:5], 0, s[12:13]
	s_add_i32 s100, s100, 1
	s_add_i32 s98, s98, s40
	s_cmp_lt_i32 s98, 0x4000
	s_cbranch_scc0 .Lrms_done
	s_add_i32 s99, s98, s40
	s_cmp_lt_i32 s99, 0x4000
	s_cbranch_scc0 .Lrms_np_b
	v_lshl_add_u64 v[6:7], v[6:7], 0, s[14:15]
	global_load_dwordx4 v[16:19], v[6:7], off offset:-3072 nt
	global_load_dwordx4 v[20:23], v[6:7], off offset:-2048 nt
	global_load_dwordx4 v[24:27], v[6:7], off offset:-1024 nt
	global_load_dwordx4 v[28:31], v[6:7], off nt
	s_cmp_eq_u32 s100, 0
	s_cbranch_scc1 .Lrms_w4_b
	s_waitcnt vmcnt(8)
	s_branch .Lrms_go_b

; #define LAS __attribute__((address_space(3)))
; __device__ __forceinline__ unsigned pk2(float lo, float hi) { f32x2 v = {lo, hi}; bf16x2_t b = __builtin_convertvector(v, bf16x2_t); return __builtin_bit_cast(unsigned, b); }
; __device__ __forceinline__ void transpose_item(const float* W, int K, int N, bf16* WT, const float* gain, LAS float* scr, int item, int nblk, int lane) {
;     const int kb = item / nblk, nb = item % nblk, k0 = 64 * kb, n0 = 64 * nb;
;     const int kr = lane >> 4, nc = 4 * (lane & 15);
;     const bool ok = (n0 + nc) < N;
;     f32x4 v[16];
; #pragma unroll
;     for (int i = 0; i < 16; ++i) { v[i] = (f32x4){0.f, 0.f, 0.f, 0.f}; if (ok) v[i] = *(const f32x4*)(W + (size_t)(k0 + 4 * i + kr) * N + n0 + nc); }
;     if (gain) {
; #pragma unroll
;         for (int i = 0; i < 16; ++i) v[i] = v[i] * gain[k0 + 4 * i + kr]; }
; #pragma unroll
;     for (int i = 0; i < 16; ++i) { LAS float* d = scr + (4 * i + kr) * 65 + nc; d[0] = v[i].x; d[1] = v[i].y; d[2] = v[i].z; d[3] = v[i].w; }
;     asm volatile("s_waitcnt lgkmcnt(0)" ::: "memory");
;     const int c = lane & 7;
; #pragma unroll
;     for (int j = 0; j < 8; ++j) { const int n = (lane >> 3) + 8 * j; const LAS float* sp = scr + (8 * c) * 65 + n;
;         u32x4 o; o.x = pk2(sp[0 * 65], sp[1 * 65]); o.y = pk2(sp[2 * 65], sp[3 * 65]); o.z = pk2(sp[4 * 65], sp[5 * 65]); o.w = pk2(sp[6 * 65], sp[7 * 65]);
;         *(u32x4*)(WT + (size_t)(n0 + n) * K + k0 + 8 * c) = o; }
; __device__ __forceinline__ void p0b_mlp_weights(const Args& a, LAS unsigned char* lds) {
;     ...
;         else transpose_item(a.w_dn, FF, D_, (bf16*)(a.ws + WS_WDN), nullptr, scr, it - I_UP, D_ / 64, lane);
.Lw1_517:
	s_movk_i32 s24, 0x3ff
	v_cmp_lt_i32_e32 vcc, s24, v84
	v_add_u32_e32 v77, 0x34d8, v98
	v_add_u32_e32 v125, 0x38e0, v98
	v_add_u32_e32 v126, 0x38e8, v98
	v_add_u32_e32 v127, 0x3cf0, v98
	v_add_u32_e32 v128, 0x3cf8, v98
	v_add_u32_e32 v124, 0x400, v88
	s_and_saveexec_b64 s[24:25], vcc
	s_xor_b64 s[44:45], exec, s[24:25]
	s_cbranch_execz .Lw1_519
	v_and_b32_e32 v1, 0x3ffc0, v97
	v_and_b32_e32 v66, 0x3c0, v96
	v_or_b32_e32 v4, v1, v85
	v_lshlrev_b32_e32 v2, 2, v66
	v_mov_b32_e32 v3, v0
	v_lshl_add_u64 v[2:3], v[68:69], 0, v[2:3]
	v_lshlrev_b32_e32 v4, 12, v4
	v_mov_b32_e32 v5, v0
	v_lshl_add_u64 v[62:63], v[2:3], 0, v[4:5]
	v_add_co_u32_e32 v6, vcc, 0x4000, v62
	s_nop 1
	v_addc_co_u32_e32 v7, vcc, 0, v63, vcc
	v_add_co_u32_e32 v10, vcc, 0x8000, v62
	global_load_dwordx4 v[2:5], v[62:63], off nt
	s_nop 0
	global_load_dwordx4 v[6:9], v[6:7], off nt
	v_addc_co_u32_e32 v11, vcc, 0, v63, vcc
	v_add_co_u32_e32 v14, vcc, 0xc000, v62
	s_nop 1
	v_addc_co_u32_e32 v15, vcc, 0, v63, vcc
	v_add_co_u32_e32 v18, vcc, 0x10000, v62
	global_load_dwordx4 v[10:13], v[10:11], off nt
	s_nop 0
	global_load_dwordx4 v[14:17], v[14:15], off nt
	v_addc_co_u32_e32 v19, vcc, 0, v63, vcc
	v_add_co_u32_e32 v22, vcc, 0x14000, v62
	s_nop 1
	v_addc_co_u32_e32 v23, vcc, 0, v63, vcc
	v_add_co_u32_e32 v26, vcc, 0x18000, v62
	global_load_dwordx4 v[18:21], v[18:19], off nt
	s_nop 0
	global_load_dwordx4 v[22:25], v[22:23], off nt
	v_addc_co_u32_e32 v27, vcc, 0, v63, vcc
	v_add_co_u32_e32 v30, vcc, 0x1c000, v62
	s_nop 1
	v_addc_co_u32_e32 v31, vcc, 0, v63, vcc
	v_add_co_u32_e32 v34, vcc, 0x20000, v62
	global_load_dwordx4 v[26:29], v[26:27], off nt
	s_nop 0
	global_load_dwordx4 v[30:33], v[30:31], off nt
	v_addc_co_u32_e32 v35, vcc, 0, v63, vcc
	v_add_co_u32_e32 v38, vcc, 0x24000, v62
	s_nop 1
	v_addc_co_u32_e32 v39, vcc, 0, v63, vcc
	v_add_co_u32_e32 v42, vcc, 0x28000, v62
	global_load_dwordx4 v[34:37], v[34:35], off nt
	s_nop 0
	global_load_dwordx4 v[38:41], v[38:39], off nt
	v_addc_co_u32_e32 v43, vcc, 0, v63, vcc
	v_add_co_u32_e32 v46, vcc, 0x2c000, v62
	s_nop 1
	v_addc_co_u32_e32 v47, vcc, 0, v63, vcc
	v_add_co_u32_e32 v50, vcc, 0x30000, v62
	global_load_dwordx4 v[42:45], v[42:43], off nt
	s_nop 0
	global_load_dwordx4 v[46:49], v[46:47], off nt
	v_addc_co_u32_e32 v51, vcc, 0, v63, vcc
	v_add_co_u32_e32 v54, vcc, 0x34000, v62
	s_nop 1
	v_addc_co_u32_e32 v55, vcc, 0, v63, vcc
	global_load_dwordx4 v[50:53], v[50:51], off nt
	s_nop 0
	global_load_dwordx4 v[54:57], v[54:55], off nt
	v_add_co_u32_e32 v58, vcc, 0x38000, v62
	s_nop 1
	v_addc_co_u32_e32 v59, vcc, 0, v63, vcc
	global_load_dwordx4 v[58:61], v[58:59], off nt
	v_add_co_u32_e32 v62, vcc, 0x3c000, v62
	s_nop 1
	v_addc_co_u32_e32 v63, vcc, 0, v63, vcc
	global_load_dwordx4 v[62:65], v[62:63], off nt
	s_waitcnt vmcnt(15)
	ds_write2_b32 v98, v2, v3 offset1:1
	ds_write2_b32 v98, v4, v5 offset0:2 offset1:3
	s_waitcnt vmcnt(14)
	ds_write2_b32 v99, v6, v7 offset1:1
	ds_write2_b32 v100, v8, v9 offset1:1
	s_waitcnt vmcnt(13)
	ds_write2_b32 v101, v10, v11 offset1:1
	ds_write2_b32 v102, v12, v13 offset1:1
	s_waitcnt vmcnt(12)
	ds_write2_b32 v103, v14, v15 offset1:1
	ds_write2_b32 v104, v16, v17 offset1:1
	s_waitcnt vmcnt(11)
	ds_write2_b32 v105, v18, v19 offset1:1
	ds_write2_b32 v106, v20, v21 offset1:1
	s_waitcnt vmcnt(10)
	ds_write2_b32 v107, v22, v23 offset1:1
	ds_write2_b32 v108, v24, v25 offset1:1
	s_waitcnt vmcnt(9)
	ds_write2_b32 v109, v26, v27 offset1:1
	ds_write2_b32 v110, v28, v29 offset1:1
	s_waitcnt vmcnt(8)
	ds_write2_b32 v111, v30, v31 offset1:1
	ds_write2_b32 v112, v32, v33 offset1:1
	s_waitcnt vmcnt(7)
	ds_write2_b32 v113, v34, v35 offset1:1
	ds_write2_b32 v114, v36, v37 offset1:1
	s_waitcnt vmcnt(6)
	ds_write2_b32 v115, v38, v39 offset1:1
	ds_write2_b32 v116, v40, v41 offset1:1
	s_waitcnt vmcnt(5)
	ds_write2_b32 v117, v42, v43 offset1:1
	ds_write2_b32 v118, v44, v45 offset1:1
	s_waitcnt vmcnt(4)
	ds_write2_b32 v119, v46, v47 offset1:1
	ds_write2_b32 v120, v48, v49 offset1:1
	s_waitcnt vmcnt(3)
	ds_write2_b32 v121, v50, v51 offset1:1
	ds_write2_b32 v122, v52, v53 offset1:1
	s_waitcnt vmcnt(2)
	ds_write2_b32 v123, v54, v55 offset1:1
	ds_write2_b32 v77, v56, v57 offset1:1
	s_waitcnt vmcnt(1)
	ds_write2_b32 v125, v58, v59 offset1:1
	ds_write2_b32 v126, v60, v61 offset1:1
	s_waitcnt vmcnt(0)
	ds_write2_b32 v127, v62, v63 offset1:1
	ds_write2_b32 v128, v64, v65 offset1:1
	s_waitcnt lgkmcnt(0)
	ds_read2_b32 v[6:7], v88 offset0:65 offset1:73
	ds_read2_b32 v[8:9], v88 offset1:8
	ds_read2_b32 v[10:11], v88 offset0:130 offset1:138
	ds_read2_b32 v[12:13], v88 offset0:195 offset1:203
	ds_read2_b32 v[14:15], v124 offset0:4 offset1:12
	ds_read2_b32 v[16:17], v124 offset0:69 offset1:77
	ds_read2_b32 v[18:19], v124 offset0:134 offset1:142
	ds_read2_b32 v[20:21], v124 offset0:199 offset1:207
	v_lshlrev_b32_e32 v2, 1, v1
	v_mov_b32_e32 v3, v0
	v_or_b32_e32 v1, v66, v87
	v_lshl_add_u64 v[22:23], v[72:73], 0, v[2:3]
	v_lshlrev_b32_e32 v24, 13, v1
	v_mov_b32_e32 v25, v0
	s_waitcnt lgkmcnt(6)
	v_cvt_pk_bf16_f32 v2, v8, v6
	s_waitcnt lgkmcnt(4)
	v_cvt_pk_bf16_f32 v3, v10, v12
	s_waitcnt lgkmcnt(2)
	v_cvt_pk_bf16_f32 v4, v14, v16
	s_waitcnt lgkmcnt(0)
	v_cvt_pk_bf16_f32 v5, v18, v20
	v_lshl_add_u64 v[24:25], v[22:23], 0, v[24:25]
	global_store_dwordx4 v[24:25], v[2:5], off
	v_or_b32_e32 v1, v66, v89
	v_lshlrev_b32_e32 v6, 13, v1
	v_cvt_pk_bf16_f32 v2, v9, v7
	v_cvt_pk_bf16_f32 v3, v11, v13
	v_cvt_pk_bf16_f32 v4, v15, v17
	v_cvt_pk_bf16_f32 v5, v19, v21
	ds_read2_b32 v[8:9], v88 offset0:81 offset1:89
	ds_read2_b32 v[10:11], v88 offset0:16 offset1:24
	ds_read2_b32 v[12:13], v88 offset0:146 offset1:154
	ds_read2_b32 v[14:15], v88 offset0:211 offset1:219
	ds_read2_b32 v[16:17], v124 offset0:20 offset1:28
	ds_read2_b32 v[18:19], v124 offset0:85 offset1:93
	ds_read2_b32 v[20:21], v124 offset0:150 offset1:158
	ds_read2_b32 v[24:25], v124 offset0:215 offset1:223
	v_mov_b32_e32 v7, v0
	v_lshl_add_u64 v[6:7], v[22:23], 0, v[6:7]
	v_or_b32_e32 v1, v66, v90
	global_store_dwordx4 v[6:7], v[2:5], off
	v_lshlrev_b32_e32 v6, 13, v1
	v_mov_b32_e32 v7, v0
	s_waitcnt lgkmcnt(6)
; #define LAS __attribute__((address_space(3)))
; __device__ __forceinline__ unsigned pk2(float lo, float hi) { f32x2 v = {lo, hi}; bf16x2_t b = __builtin_convertvector(v, bf16x2_t); return __builtin_bit_cast(unsigned, b); }
; __device__ __forceinline__ void transpose_item(const float* W, int K, int N, bf16* WT, const float* gain, LAS float* scr, int item, int nblk, int lane) {
;     const int kb = item / nblk, nb = item % nblk, k0 = 64 * kb, n0 = 64 * nb;
;     const int kr = lane >> 4, nc = 4 * (lane & 15);
;     const bool ok = (n0 + nc) < N;
;     f32x4 v[16];
; #pragma unroll
;     for (int i = 0; i < 16; ++i) { v[i] = (f32x4){0.f, 0.f, 0.f, 0.f}; if (ok) v[i] = *(const f32x4*)(W + (size_t)(k0 + 4 * i + kr) * N + n0 + nc); }
;     if (gain) {
; #pragma unroll
;         for (int i = 0; i < 16; ++i) v[i] = v[i] * gain[k0 + 4 * i + kr]; }
; #pragma unroll
;     for (int i = 0; i < 16; ++i) { LAS float* d = scr + (4 * i + kr) * 65 + nc; d[0] = v[i].x; d[1] = v[i].y; d[2] = v[i].z; d[3] = v[i].w; }
;     asm volatile("s_waitcnt lgkmcnt(0)" ::: "memory");
;     const int c = lane & 7;
; #pragma unroll
;     for (int j = 0; j < 8; ++j) { const int n = (lane >> 3) + 8 * j; const LAS float* sp = scr + (8 * c) * 65 + n;
;         u32x4 o; o.x = pk2(sp[0 * 65], sp[1 * 65]); o.y = pk2(sp[2 * 65], sp[3 * 65]); o.z = pk2(sp[4 * 65], sp[5 * 65]); o.w = pk2(sp[6 * 65], sp[7 * 65]);
;         *(u32x4*)(WT + (size_t)(n0 + n) * K + k0 + 8 * c) = o; }
; __device__ __forceinline__ void p0b_mlp_weights(const Args& a, LAS unsigned char* lds) {
;     ...
;         if (it < I_UP) transpose_item(a.w_up, D_, FF, (bf16*)(a.ws + WS_WUP), a.ln_mlp_g, scr, it, FF / 64, lane);
;         else transpose_item(a.w_dn, FF, D_, (bf16*)(a.ws + WS_WDN), nullptr, scr, it - I_UP, D_ / 64, lane);
	v_cvt_pk_bf16_f32 v2, v10, v8
	s_waitcnt lgkmcnt(4)
	v_cvt_pk_bf16_f32 v3, v12, v14
	s_waitcnt lgkmcnt(2)
	v_cvt_pk_bf16_f32 v4, v16, v18
	s_waitcnt lgkmcnt(0)
	v_cvt_pk_bf16_f32 v5, v20, v24
	v_lshl_add_u64 v[6:7], v[22:23], 0, v[6:7]
	global_store_dwordx4 v[6:7], v[2:5], off
	v_or_b32_e32 v1, v66, v91
	v_lshlrev_b32_e32 v6, 13, v1
	v_cvt_pk_bf16_f32 v2, v11, v9
	v_cvt_pk_bf16_f32 v3, v13, v15
	v_cvt_pk_bf16_f32 v4, v17, v19
	v_cvt_pk_bf16_f32 v5, v21, v25
	ds_read2_b32 v[8:9], v88 offset0:32 offset1:40
	ds_read2_b32 v[10:11], v88 offset0:97 offset1:105
	ds_read2_b32 v[12:13], v88 offset0:162 offset1:170
	ds_read2_b32 v[14:15], v88 offset0:227 offset1:235
	ds_read2_b32 v[16:17], v124 offset0:36 offset1:44
	ds_read2_b32 v[18:19], v124 offset0:101 offset1:109
	ds_read2_b32 v[20:21], v124 offset0:166 offset1:174
	ds_read2_b32 v[24:25], v124 offset0:231 offset1:239
	v_mov_b32_e32 v7, v0
	v_lshl_add_u64 v[6:7], v[22:23], 0, v[6:7]
	v_or_b32_e32 v1, v66, v92
	global_store_dwordx4 v[6:7], v[2:5], off
	v_lshlrev_b32_e32 v6, 13, v1
	v_mov_b32_e32 v7, v0
	s_waitcnt lgkmcnt(6)
	v_cvt_pk_bf16_f32 v2, v8, v10
	s_waitcnt lgkmcnt(4)
	v_cvt_pk_bf16_f32 v3, v12, v14
	s_waitcnt lgkmcnt(2)
	v_cvt_pk_bf16_f32 v4, v16, v18
	s_waitcnt lgkmcnt(0)
	v_cvt_pk_bf16_f32 v5, v20, v24
	v_lshl_add_u64 v[6:7], v[22:23], 0, v[6:7]
	global_store_dwordx4 v[6:7], v[2:5], off
	v_or_b32_e32 v1, v66, v93
	v_lshlrev_b32_e32 v6, 13, v1
	v_cvt_pk_bf16_f32 v2, v9, v11
	v_cvt_pk_bf16_f32 v3, v13, v15
	v_cvt_pk_bf16_f32 v4, v17, v19
	v_cvt_pk_bf16_f32 v5, v21, v25
	ds_read2_b32 v[8:9], v88 offset0:48 offset1:56
	ds_read2_b32 v[10:11], v88 offset0:113 offset1:121
	ds_read2_b32 v[12:13], v88 offset0:178 offset1:186
	ds_read2_b32 v[14:15], v88 offset0:243 offset1:251
	ds_read2_b32 v[16:17], v124 offset0:52 offset1:60
	ds_read2_b32 v[18:19], v124 offset0:117 offset1:125
	ds_read2_b32 v[20:21], v124 offset0:182 offset1:190
	ds_read2_b32 v[24:25], v124 offset0:247 offset1:255
	v_mov_b32_e32 v7, v0
	v_lshl_add_u64 v[6:7], v[22:23], 0, v[6:7]
	v_or_b32_e32 v1, v66, v94
	global_store_dwordx4 v[6:7], v[2:5], off
	v_lshlrev_b32_e32 v6, 13, v1
	v_mov_b32_e32 v7, v0
	s_waitcnt lgkmcnt(6)
	v_cvt_pk_bf16_f32 v2, v8, v10
	s_waitcnt lgkmcnt(4)
	v_cvt_pk_bf16_f32 v3, v12, v14
	s_waitcnt lgkmcnt(2)
	v_cvt_pk_bf16_f32 v4, v16, v18
	s_waitcnt lgkmcnt(0)
	v_cvt_pk_bf16_f32 v5, v20, v24
	v_lshl_add_u64 v[6:7], v[22:23], 0, v[6:7]
	v_or_b32_e32 v1, v66, v95
	global_store_dwordx4 v[6:7], v[2:5], off
	v_lshlrev_b32_e32 v6, 13, v1
	v_mov_b32_e32 v7, v0
	v_cvt_pk_bf16_f32 v2, v9, v11
	v_cvt_pk_bf16_f32 v3, v13, v15
	v_cvt_pk_bf16_f32 v4, v17, v19
	v_cvt_pk_bf16_f32 v5, v21, v25
	v_lshl_add_u64 v[6:7], v[22:23], 0, v[6:7]
	global_store_dwordx4 v[6:7], v[2:5], off
	s_waitcnt lgkmcnt(0)
.Lw1_519:
	s_andn2_saveexec_b64 s[44:45], s[44:45]
	s_cbranch_execz .Lw1_516
	v_ashrrev_i32_e32 v1, 31, v84
	v_lshrrev_b32_e32 v1, 26, v1
	v_add_u32_e32 v1, v84, v1
	v_and_b32_e32 v76, 0xffffffc0, v1
	v_lshlrev_b32_e32 v1, 6, v1
	v_and_b32_e32 v129, 0xfffff000, v1
	v_sub_u32_e32 v2, v96, v129
	v_mov_b32_e32 v6, v0
	v_mov_b32_e32 v7, v0
	v_add_u32_e32 v1, v2, v86
	s_movk_i32 s24, 0x1000
	v_or_b32_e32 v78, v76, v85
	v_ashrrev_i32_e32 v3, 31, v2
	v_mov_b32_e32 v4, v0
	v_mov_b32_e32 v5, v0
	v_mov_b64_e32 v[10:11], v[6:7]
	v_cmp_gt_i32_e32 vcc, s24, v1
	v_lshl_add_u64 v[80:81], v[2:3], 2, v[70:71]
	v_ashrrev_i32_e32 v79, 31, v78
	v_mov_b64_e32 v[8:9], v[4:5]
	s_and_saveexec_b64 s[24:25], vcc
	s_cbranch_execz .Lw1_522
	v_lshlrev_b64 v[2:3], 14, v[78:79]
	v_lshl_add_u64 v[2:3], v[80:81], 0, v[2:3]
	global_load_dwordx4 v[8:11], v[2:3], off nt
.Lw1_522:
	s_or_b64 exec, exec, s[24:25]
	s_and_saveexec_b64 s[24:25], vcc
	s_cbranch_execz .Lw1_524
	v_or_b32_e32 v2, 4, v78
	v_ashrrev_i32_e32 v3, 31, v2
	v_lshlrev_b64 v[2:3], 14, v[2:3]
	v_lshl_add_u64 v[2:3], v[80:81], 0, v[2:3]
	global_load_dwordx4 v[4:7], v[2:3], off nt
.Lw1_524:
	s_or_b64 exec, exec, s[24:25]
	v_mov_b32_e32 v2, v0
	v_mov_b32_e32 v3, v0
	v_mov_b32_e32 v1, v0
	v_mov_b64_e32 v[14:15], v[2:3]
	v_mov_b64_e32 v[12:13], v[0:1]
	s_and_saveexec_b64 s[24:25], vcc
	s_cbranch_execz .Lw1_526
	v_or_b32_e32 v12, 8, v78
	v_ashrrev_i32_e32 v13, 31, v12
	v_lshlrev_b64 v[12:13], 14, v[12:13]
	v_lshl_add_u64 v[12:13], v[80:81], 0, v[12:13]
	global_load_dwordx4 v[12:15], v[12:13], off nt
.Lw1_526:
	s_or_b64 exec, exec, s[24:25]
	v_mov_b64_e32 v[18:19], v[2:3]
	v_mov_b64_e32 v[16:17], v[0:1]
	s_and_saveexec_b64 s[24:25], vcc
	s_cbranch_execz .Lw1_528
	v_or_b32_e32 v2, 12, v78
	v_ashrrev_i32_e32 v3, 31, v2
	v_lshlrev_b64 v[2:3], 14, v[2:3]
	v_lshl_add_u64 v[2:3], v[80:81], 0, v[2:3]
	global_load_dwordx4 v[16:19], v[2:3], off nt
; #define LAS __attribute__((address_space(3)))
; __device__ __forceinline__ void transpose_item(const float* W, int K, int N, bf16* WT, const float* gain, LAS float* scr, int item, int nblk, int lane) {
;     const int kb = item / nblk, nb = item % nblk, k0 = 64 * kb, n0 = 64 * nb;
;     const int kr = lane >> 4, nc = 4 * (lane & 15);
;     const bool ok = (n0 + nc) < N;
;     f32x4 v[16];
; #pragma unroll
;     for (int i = 0; i < 16; ++i) { v[i] = (f32x4){0.f, 0.f, 0.f, 0.f}; if (ok) v[i] = *(const f32x4*)(W + (size_t)(k0 + 4 * i + kr) * N + n0 + nc); }
; __device__ __forceinline__ void p0b_mlp_weights(const Args& a, LAS unsigned char* lds) {
;     ...
;         if (it < I_UP) transpose_item(a.w_up, D_, FF, (bf16*)(a.ws + WS_WUP), a.ln_mlp_g, scr, it, FF / 64, lane);
.Lw1_528:
	s_or_b64 exec, exec, s[24:25]
	v_mov_b32_e32 v2, v0
	v_mov_b32_e32 v3, v0
	v_mov_b32_e32 v1, v0
	v_mov_b64_e32 v[22:23], v[2:3]
	v_mov_b64_e32 v[20:21], v[0:1]
	s_and_saveexec_b64 s[24:25], vcc
	s_cbranch_execz .Lw1_530
	v_or_b32_e32 v20, 16, v78
	v_ashrrev_i32_e32 v21, 31, v20
	v_lshlrev_b64 v[20:21], 14, v[20:21]
	v_lshl_add_u64 v[20:21], v[80:81], 0, v[20:21]
	global_load_dwordx4 v[20:23], v[20:21], off nt
.Lw1_530:
	s_or_b64 exec, exec, s[24:25]
	v_mov_b64_e32 v[26:27], v[2:3]
	v_mov_b64_e32 v[24:25], v[0:1]
	s_and_saveexec_b64 s[24:25], vcc
	s_cbranch_execz .Lw1_532
	v_or_b32_e32 v2, 20, v78
	v_ashrrev_i32_e32 v3, 31, v2
	v_lshlrev_b64 v[2:3], 14, v[2:3]
	v_lshl_add_u64 v[2:3], v[80:81], 0, v[2:3]
	global_load_dwordx4 v[24:27], v[2:3], off nt
.Lw1_532:
	s_or_b64 exec, exec, s[24:25]
	v_mov_b32_e32 v2, v0
	v_mov_b32_e32 v3, v0
	v_mov_b32_e32 v1, v0
	v_mov_b64_e32 v[30:31], v[2:3]
	v_mov_b64_e32 v[28:29], v[0:1]
	s_and_saveexec_b64 s[24:25], vcc
	s_cbranch_execz .Lw1_534
	v_or_b32_e32 v28, 24, v78
	v_ashrrev_i32_e32 v29, 31, v28
	v_lshlrev_b64 v[28:29], 14, v[28:29]
	v_lshl_add_u64 v[28:29], v[80:81], 0, v[28:29]
	global_load_dwordx4 v[28:31], v[28:29], off nt
.Lw1_534:
	s_or_b64 exec, exec, s[24:25]
	v_mov_b64_e32 v[34:35], v[2:3]
	v_mov_b64_e32 v[32:33], v[0:1]
	s_and_saveexec_b64 s[24:25], vcc
	s_cbranch_execz .Lw1_536
	v_or_b32_e32 v2, 28, v78
	v_ashrrev_i32_e32 v3, 31, v2
	v_lshlrev_b64 v[2:3], 14, v[2:3]
	v_lshl_add_u64 v[2:3], v[80:81], 0, v[2:3]
	global_load_dwordx4 v[32:35], v[2:3], off nt
.Lw1_536:
	s_or_b64 exec, exec, s[24:25]
	v_mov_b32_e32 v2, v0
	v_mov_b32_e32 v3, v0
	v_mov_b32_e32 v1, v0
	v_mov_b64_e32 v[38:39], v[2:3]
	v_mov_b64_e32 v[36:37], v[0:1]
	s_and_saveexec_b64 s[24:25], vcc
	s_cbranch_execz .Lw1_538
	v_or_b32_e32 v36, 32, v78
	v_ashrrev_i32_e32 v37, 31, v36
	v_lshlrev_b64 v[36:37], 14, v[36:37]
	v_lshl_add_u64 v[36:37], v[80:81], 0, v[36:37]
	global_load_dwordx4 v[36:39], v[36:37], off nt
.Lw1_538:
	s_or_b64 exec, exec, s[24:25]
	v_mov_b64_e32 v[42:43], v[2:3]
	v_mov_b64_e32 v[40:41], v[0:1]
	s_and_saveexec_b64 s[24:25], vcc
	s_cbranch_execz .Lw1_540
	v_or_b32_e32 v2, 36, v78
	v_ashrrev_i32_e32 v3, 31, v2
	v_lshlrev_b64 v[2:3], 14, v[2:3]
	v_lshl_add_u64 v[2:3], v[80:81], 0, v[2:3]
	global_load_dwordx4 v[40:43], v[2:3], off nt
.Lw1_540:
	s_or_b64 exec, exec, s[24:25]
	v_mov_b32_e32 v2, v0
	v_mov_b32_e32 v3, v0
	v_mov_b32_e32 v1, v0
	v_mov_b64_e32 v[46:47], v[2:3]
	v_mov_b64_e32 v[44:45], v[0:1]
	s_and_saveexec_b64 s[24:25], vcc
	s_cbranch_execz .Lw1_542
	v_or_b32_e32 v44, 40, v78
	v_ashrrev_i32_e32 v45, 31, v44
	v_lshlrev_b64 v[44:45], 14, v[44:45]
	v_lshl_add_u64 v[44:45], v[80:81], 0, v[44:45]
	global_load_dwordx4 v[44:47], v[44:45], off nt
.Lw1_542:
	s_or_b64 exec, exec, s[24:25]
	v_mov_b64_e32 v[50:51], v[2:3]
	v_mov_b64_e32 v[48:49], v[0:1]
	s_and_saveexec_b64 s[24:25], vcc
	s_cbranch_execz .Lw1_544
	v_or_b32_e32 v2, 44, v78
	v_ashrrev_i32_e32 v3, 31, v2
	v_lshlrev_b64 v[2:3], 14, v[2:3]
	v_lshl_add_u64 v[2:3], v[80:81], 0, v[2:3]
	global_load_dwordx4 v[48:51], v[2:3], off nt
.Lw1_544:
	s_or_b64 exec, exec, s[24:25]
	v_mov_b32_e32 v2, v0
	v_mov_b32_e32 v3, v0
	v_mov_b32_e32 v1, v0
	v_mov_b64_e32 v[54:55], v[2:3]
	v_mov_b64_e32 v[52:53], v[0:1]
	s_and_saveexec_b64 s[24:25], vcc
	s_cbranch_execz .Lw1_546
	v_or_b32_e32 v52, 48, v78
	v_ashrrev_i32_e32 v53, 31, v52
	v_lshlrev_b64 v[52:53], 14, v[52:53]
	v_lshl_add_u64 v[52:53], v[80:81], 0, v[52:53]
	global_load_dwordx4 v[52:55], v[52:53], off nt
.Lw1_546:
	s_or_b64 exec, exec, s[24:25]
	v_mov_b64_e32 v[58:59], v[2:3]
	v_mov_b64_e32 v[56:57], v[0:1]
	s_and_saveexec_b64 s[24:25], vcc
	s_cbranch_execz .Lw1_548
	v_or_b32_e32 v2, 52, v78
	v_ashrrev_i32_e32 v3, 31, v2
	v_lshlrev_b64 v[2:3], 14, v[2:3]
	v_lshl_add_u64 v[2:3], v[80:81], 0, v[2:3]
	global_load_dwordx4 v[56:59], v[2:3], off nt
.Lw1_548:
	s_or_b64 exec, exec, s[24:25]
	v_mov_b32_e32 v2, v0
	v_mov_b32_e32 v3, v0
	v_mov_b32_e32 v1, v0
	v_mov_b64_e32 v[62:63], v[2:3]
	v_mov_b64_e32 v[60:61], v[0:1]
	s_and_saveexec_b64 s[24:25], vcc
	s_cbranch_execz .Lw1_550
	v_or_b32_e32 v60, 56, v78
	v_ashrrev_i32_e32 v61, 31, v60
	v_lshlrev_b64 v[60:61], 14, v[60:61]
	v_lshl_add_u64 v[60:61], v[80:81], 0, v[60:61]
	global_load_dwordx4 v[60:63], v[60:61], off nt
.Lw1_550:
	s_or_b64 exec, exec, s[24:25]
	v_mov_b64_e32 v[66:67], v[2:3]
	v_mov_b64_e32 v[64:65], v[0:1]
	s_and_saveexec_b64 s[24:25], vcc
	s_cbranch_execz .Lw1_552
	v_or_b32_e32 v2, 60, v78
	v_ashrrev_i32_e32 v3, 31, v2
	v_lshlrev_b64 v[2:3], 14, v[2:3]
	v_lshl_add_u64 v[2:3], v[80:81], 0, v[2:3]
	global_load_dwordx4 v[64:67], v[2:3], off nt

; #define LAS __attribute__((address_space(3)))
; __device__ __forceinline__ void transpose_item(const float* W, int K, int N, bf16* WT, const float* gain, LAS float* scr, int item, int nblk, int lane) {
;     const int kb = item / nblk, nb = item % nblk, k0 = 64 * kb, n0 = 64 * nb;
;     const int kr = lane >> 4, nc = 4 * (lane & 15);
;     const bool ok = (n0 + nc) < N;
;     f32x4 v[16];
; #pragma unroll
;     for (int i = 0; i < 16; ++i) { v[i] = (f32x4){0.f, 0.f, 0.f, 0.f}; if (ok) v[i] = *(const f32x4*)(W + (size_t)(k0 + 4 * i + kr) * N + n0 + nc); }
;     if (gain) {
; #pragma unroll
;         for (int i = 0; i < 16; ++i) v[i] = v[i] * gain[k0 + 4 * i + kr]; }
; #pragma unroll
;     for (int i = 0; i < 16; ++i) { LAS float* d = scr + (4 * i + kr) * 65 + nc; d[0] = v[i].x; d[1] = v[i].y; d[2] = v[i].z; d[3] = v[i].w; }
;     asm volatile("s_waitcnt lgkmcnt(0)" ::: "memory");
.LBB0_517:
	s_movk_i32 s24, 0x3ff
	v_cmp_lt_i32_e32 vcc, s24, v84
	v_add_u32_e32 v77, 0x34d8, v98
	v_add_u32_e32 v125, 0x38e0, v98
	v_add_u32_e32 v126, 0x38e8, v98
	v_add_u32_e32 v127, 0x3cf0, v98
	v_add_u32_e32 v128, 0x3cf8, v98
	v_add_u32_e32 v124, 0x400, v88
	s_and_saveexec_b64 s[24:25], vcc
	s_xor_b64 s[44:45], exec, s[24:25]
	s_cbranch_execz .LBB0_519
	v_and_b32_e32 v1, 0x3ffc0, v97
	v_and_b32_e32 v66, 0x3c0, v96
	v_or_b32_e32 v4, v1, v85
	v_lshlrev_b32_e32 v2, 2, v66
	v_mov_b32_e32 v3, v0
	v_lshl_add_u64 v[2:3], v[68:69], 0, v[2:3]
	v_lshlrev_b32_e32 v4, 12, v4
	v_mov_b32_e32 v5, v0
	v_lshl_add_u64 v[62:63], v[2:3], 0, v[4:5]
	v_add_co_u32_e32 v6, vcc, 0x4000, v62
	s_nop 1
	v_addc_co_u32_e32 v7, vcc, 0, v63, vcc
	v_add_co_u32_e32 v10, vcc, 0x8000, v62
	global_load_dwordx4 v[2:5], v[62:63], off nt
	s_nop 0
	global_load_dwordx4 v[6:9], v[6:7], off nt
	v_addc_co_u32_e32 v11, vcc, 0, v63, vcc
	v_add_co_u32_e32 v14, vcc, 0xc000, v62
	s_nop 1
	v_addc_co_u32_e32 v15, vcc, 0, v63, vcc
	v_add_co_u32_e32 v18, vcc, 0x10000, v62
	global_load_dwordx4 v[10:13], v[10:11], off nt
	s_nop 0
	global_load_dwordx4 v[14:17], v[14:15], off nt
	v_addc_co_u32_e32 v19, vcc, 0, v63, vcc
	v_add_co_u32_e32 v22, vcc, 0x14000, v62
	s_nop 1
	v_addc_co_u32_e32 v23, vcc, 0, v63, vcc
	v_add_co_u32_e32 v26, vcc, 0x18000, v62
	global_load_dwordx4 v[18:21], v[18:19], off nt
	s_nop 0
	global_load_dwordx4 v[22:25], v[22:23], off nt
	v_addc_co_u32_e32 v27, vcc, 0, v63, vcc
	v_add_co_u32_e32 v30, vcc, 0x1c000, v62
	s_nop 1
	v_addc_co_u32_e32 v31, vcc, 0, v63, vcc
	v_add_co_u32_e32 v34, vcc, 0x20000, v62
	global_load_dwordx4 v[26:29], v[26:27], off nt
	s_nop 0
	global_load_dwordx4 v[30:33], v[30:31], off nt
	v_addc_co_u32_e32 v35, vcc, 0, v63, vcc
	v_add_co_u32_e32 v38, vcc, 0x24000, v62
	s_nop 1
	v_addc_co_u32_e32 v39, vcc, 0, v63, vcc
	v_add_co_u32_e32 v42, vcc, 0x28000, v62
	global_load_dwordx4 v[34:37], v[34:35], off nt
	s_nop 0
	global_load_dwordx4 v[38:41], v[38:39], off nt
	v_addc_co_u32_e32 v43, vcc, 0, v63, vcc
	v_add_co_u32_e32 v46, vcc, 0x2c000, v62
	s_nop 1
	v_addc_co_u32_e32 v47, vcc, 0, v63, vcc
	v_add_co_u32_e32 v50, vcc, 0x30000, v62
	global_load_dwordx4 v[42:45], v[42:43], off nt
	s_nop 0
	global_load_dwordx4 v[46:49], v[46:47], off nt
	v_addc_co_u32_e32 v51, vcc, 0, v63, vcc
	v_add_co_u32_e32 v54, vcc, 0x34000, v62
	s_nop 1
	v_addc_co_u32_e32 v55, vcc, 0, v63, vcc
	global_load_dwordx4 v[50:53], v[50:51], off nt
	s_nop 0
	global_load_dwordx4 v[54:57], v[54:55], off nt
	v_add_co_u32_e32 v58, vcc, 0x38000, v62
	s_nop 1
	v_addc_co_u32_e32 v59, vcc, 0, v63, vcc
	global_load_dwordx4 v[58:61], v[58:59], off nt
	v_add_co_u32_e32 v62, vcc, 0x3c000, v62
	s_nop 1
	v_addc_co_u32_e32 v63, vcc, 0, v63, vcc
	global_load_dwordx4 v[62:65], v[62:63], off nt
	s_waitcnt vmcnt(15)
	ds_write2_b32 v98, v2, v3 offset1:1
	ds_write2_b32 v98, v4, v5 offset0:2 offset1:3
	s_waitcnt vmcnt(14)
	ds_write2_b32 v99, v6, v7 offset1:1
	ds_write2_b32 v100, v8, v9 offset1:1
	s_waitcnt vmcnt(13)
	ds_write2_b32 v101, v10, v11 offset1:1
	ds_write2_b32 v102, v12, v13 offset1:1
	s_waitcnt vmcnt(12)
	ds_write2_b32 v103, v14, v15 offset1:1
	ds_write2_b32 v104, v16, v17 offset1:1
	s_waitcnt vmcnt(11)
	ds_write2_b32 v105, v18, v19 offset1:1
	ds_write2_b32 v106, v20, v21 offset1:1
	s_waitcnt vmcnt(10)
	ds_write2_b32 v107, v22, v23 offset1:1
	ds_write2_b32 v108, v24, v25 offset1:1
	s_waitcnt vmcnt(9)
	ds_write2_b32 v109, v26, v27 offset1:1
	ds_write2_b32 v110, v28, v29 offset1:1
	s_waitcnt vmcnt(8)
	ds_write2_b32 v111, v30, v31 offset1:1
	ds_write2_b32 v112, v32, v33 offset1:1
	s_waitcnt vmcnt(7)
	ds_write2_b32 v113, v34, v35 offset1:1
	ds_write2_b32 v114, v36, v37 offset1:1
	s_waitcnt vmcnt(6)
	ds_write2_b32 v115, v38, v39 offset1:1
	ds_write2_b32 v116, v40, v41 offset1:1
	s_waitcnt vmcnt(5)
	ds_write2_b32 v117, v42, v43 offset1:1
	ds_write2_b32 v118, v44, v45 offset1:1
	s_waitcnt vmcnt(4)
	ds_write2_b32 v119, v46, v47 offset1:1
	ds_write2_b32 v120, v48, v49 offset1:1
	s_waitcnt vmcnt(3)
	ds_write2_b32 v121, v50, v51 offset1:1
	ds_write2_b32 v122, v52, v53 offset1:1
	s_waitcnt vmcnt(2)
	ds_write2_b32 v123, v54, v55 offset1:1
	ds_write2_b32 v77, v56, v57 offset1:1
	s_waitcnt vmcnt(1)
	ds_write2_b32 v125, v58, v59 offset1:1
	ds_write2_b32 v126, v60, v61 offset1:1
	s_waitcnt vmcnt(0)
	ds_write2_b32 v127, v62, v63 offset1:1
	ds_write2_b32 v128, v64, v65 offset1:1
	s_waitcnt lgkmcnt(0)
; #define LAS __attribute__((address_space(3)))
; __device__ __forceinline__ unsigned pk2(float lo, float hi) { f32x2 v = {lo, hi}; bf16x2_t b = __builtin_convertvector(v, bf16x2_t); return __builtin_bit_cast(unsigned, b); }
; __device__ __forceinline__ void transpose_item(const float* W, int K, int N, bf16* WT, const float* gain, LAS float* scr, int item, int nblk, int lane) {
;     ...
;     const int c = lane & 7;
; #pragma unroll
;     for (int j = 0; j < 8; ++j) { const int n = (lane >> 3) + 8 * j; const LAS float* sp = scr + (8 * c) * 65 + n;
;         u32x4 o; o.x = pk2(sp[0 * 65], sp[1 * 65]); o.y = pk2(sp[2 * 65], sp[3 * 65]); o.z = pk2(sp[4 * 65], sp[5 * 65]); o.w = pk2(sp[6 * 65], sp[7 * 65]);
;         *(u32x4*)(WT + (size_t)(n0 + n) * K + k0 + 8 * c) = o; }
;     asm volatile("s_waitcnt lgkmcnt(0)" ::: "memory");
	ds_read2_b32 v[6:7], v88 offset0:65 offset1:73
	ds_read2_b32 v[8:9], v88 offset1:8
	ds_read2_b32 v[10:11], v88 offset0:130 offset1:138
	ds_read2_b32 v[12:13], v88 offset0:195 offset1:203
	ds_read2_b32 v[14:15], v124 offset0:4 offset1:12
	ds_read2_b32 v[16:17], v124 offset0:69 offset1:77
	ds_read2_b32 v[18:19], v124 offset0:134 offset1:142
	ds_read2_b32 v[20:21], v124 offset0:199 offset1:207
	v_lshlrev_b32_e32 v2, 1, v1
	v_mov_b32_e32 v3, v0
	v_or_b32_e32 v1, v66, v87
	v_lshl_add_u64 v[22:23], v[72:73], 0, v[2:3]
	v_lshlrev_b32_e32 v24, 13, v1
	v_mov_b32_e32 v25, v0
	s_waitcnt lgkmcnt(6)
	v_cvt_pk_bf16_f32 v2, v8, v6
	s_waitcnt lgkmcnt(4)
	v_cvt_pk_bf16_f32 v3, v10, v12
	s_waitcnt lgkmcnt(2)
	v_cvt_pk_bf16_f32 v4, v14, v16
	s_waitcnt lgkmcnt(0)
	v_cvt_pk_bf16_f32 v5, v18, v20
	v_lshl_add_u64 v[24:25], v[22:23], 0, v[24:25]
	global_store_dwordx4 v[24:25], v[2:5], off sc0 sc1
	v_or_b32_e32 v1, v66, v89
	v_lshlrev_b32_e32 v6, 13, v1
	v_cvt_pk_bf16_f32 v2, v9, v7
	v_cvt_pk_bf16_f32 v3, v11, v13
	v_cvt_pk_bf16_f32 v4, v15, v17
	v_cvt_pk_bf16_f32 v5, v19, v21
	ds_read2_b32 v[8:9], v88 offset0:81 offset1:89
	ds_read2_b32 v[10:11], v88 offset0:16 offset1:24
	ds_read2_b32 v[12:13], v88 offset0:146 offset1:154
	ds_read2_b32 v[14:15], v88 offset0:211 offset1:219
	ds_read2_b32 v[16:17], v124 offset0:20 offset1:28
	ds_read2_b32 v[18:19], v124 offset0:85 offset1:93
	ds_read2_b32 v[20:21], v124 offset0:150 offset1:158
	ds_read2_b32 v[24:25], v124 offset0:215 offset1:223
	v_mov_b32_e32 v7, v0
	v_lshl_add_u64 v[6:7], v[22:23], 0, v[6:7]
	v_or_b32_e32 v1, v66, v90
	global_store_dwordx4 v[6:7], v[2:5], off sc0 sc1
	v_lshlrev_b32_e32 v6, 13, v1
	v_mov_b32_e32 v7, v0
	s_waitcnt lgkmcnt(6)
	v_cvt_pk_bf16_f32 v2, v10, v8
	s_waitcnt lgkmcnt(4)
	v_cvt_pk_bf16_f32 v3, v12, v14
	s_waitcnt lgkmcnt(2)
	v_cvt_pk_bf16_f32 v4, v16, v18
	s_waitcnt lgkmcnt(0)
	v_cvt_pk_bf16_f32 v5, v20, v24
	v_lshl_add_u64 v[6:7], v[22:23], 0, v[6:7]
	global_store_dwordx4 v[6:7], v[2:5], off sc0 sc1
	v_or_b32_e32 v1, v66, v91
	v_lshlrev_b32_e32 v6, 13, v1
	v_cvt_pk_bf16_f32 v2, v11, v9
	v_cvt_pk_bf16_f32 v3, v13, v15
	v_cvt_pk_bf16_f32 v4, v17, v19
	v_cvt_pk_bf16_f32 v5, v21, v25
	ds_read2_b32 v[8:9], v88 offset0:32 offset1:40
	ds_read2_b32 v[10:11], v88 offset0:97 offset1:105
	ds_read2_b32 v[12:13], v88 offset0:162 offset1:170
	ds_read2_b32 v[14:15], v88 offset0:227 offset1:235
	ds_read2_b32 v[16:17], v124 offset0:36 offset1:44
	ds_read2_b32 v[18:19], v124 offset0:101 offset1:109
	ds_read2_b32 v[20:21], v124 offset0:166 offset1:174
	ds_read2_b32 v[24:25], v124 offset0:231 offset1:239
	v_mov_b32_e32 v7, v0
	v_lshl_add_u64 v[6:7], v[22:23], 0, v[6:7]
	v_or_b32_e32 v1, v66, v92
	global_store_dwordx4 v[6:7], v[2:5], off sc0 sc1
	v_lshlrev_b32_e32 v6, 13, v1
	v_mov_b32_e32 v7, v0
	s_waitcnt lgkmcnt(6)
	v_cvt_pk_bf16_f32 v2, v8, v10
	s_waitcnt lgkmcnt(4)
	v_cvt_pk_bf16_f32 v3, v12, v14
	s_waitcnt lgkmcnt(2)
	v_cvt_pk_bf16_f32 v4, v16, v18
	s_waitcnt lgkmcnt(0)
	v_cvt_pk_bf16_f32 v5, v20, v24
	v_lshl_add_u64 v[6:7], v[22:23], 0, v[6:7]
	global_store_dwordx4 v[6:7], v[2:5], off sc0 sc1
	v_or_b32_e32 v1, v66, v93
	v_lshlrev_b32_e32 v6, 13, v1
	v_cvt_pk_bf16_f32 v2, v9, v11
	v_cvt_pk_bf16_f32 v3, v13, v15
	v_cvt_pk_bf16_f32 v4, v17, v19
	v_cvt_pk_bf16_f32 v5, v21, v25
	ds_read2_b32 v[8:9], v88 offset0:48 offset1:56
	ds_read2_b32 v[10:11], v88 offset0:113 offset1:121
	ds_read2_b32 v[12:13], v88 offset0:178 offset1:186
	ds_read2_b32 v[14:15], v88 offset0:243 offset1:251
	ds_read2_b32 v[16:17], v124 offset0:52 offset1:60
	ds_read2_b32 v[18:19], v124 offset0:117 offset1:125
	ds_read2_b32 v[20:21], v124 offset0:182 offset1:190
	ds_read2_b32 v[24:25], v124 offset0:247 offset1:255
	v_mov_b32_e32 v7, v0
	v_lshl_add_u64 v[6:7], v[22:23], 0, v[6:7]
	v_or_b32_e32 v1, v66, v94
	global_store_dwordx4 v[6:7], v[2:5], off sc0 sc1
	v_lshlrev_b32_e32 v6, 13, v1
	v_mov_b32_e32 v7, v0
	s_waitcnt lgkmcnt(6)
	v_cvt_pk_bf16_f32 v2, v8, v10
	s_waitcnt lgkmcnt(4)
	v_cvt_pk_bf16_f32 v3, v12, v14
	s_waitcnt lgkmcnt(2)
	v_cvt_pk_bf16_f32 v4, v16, v18
	s_waitcnt lgkmcnt(0)
	v_cvt_pk_bf16_f32 v5, v20, v24
	v_lshl_add_u64 v[6:7], v[22:23], 0, v[6:7]
	v_or_b32_e32 v1, v66, v95
	global_store_dwordx4 v[6:7], v[2:5], off sc0 sc1
	v_lshlrev_b32_e32 v6, 13, v1
	v_mov_b32_e32 v7, v0
	v_cvt_pk_bf16_f32 v2, v9, v11
	v_cvt_pk_bf16_f32 v3, v13, v15
	v_cvt_pk_bf16_f32 v4, v17, v19
	v_cvt_pk_bf16_f32 v5, v21, v25
	v_lshl_add_u64 v[6:7], v[22:23], 0, v[6:7]
	global_store_dwordx4 v[6:7], v[2:5], off sc0 sc1
	s_waitcnt lgkmcnt(0)

; __device__ __forceinline__ unsigned pk2(float lo, float hi) { f32x2 v = {lo, hi}; bf16x2_t b = __builtin_convertvector(v, bf16x2_t); return __builtin_bit_cast(unsigned, b); }
; __device__ __forceinline__ float ex2(float x) { return __builtin_amdgcn_exp2f(x); }
; __device__ __forceinline__ void ssd_state_scan(const Args& a) {
;     ...
;     for (int e = blockIdx.x * NTHREADS + tid; e < NB * 8 * 2 * 1024; e += gridDim.x * NTHREADS) {
;         const int seq = e >> 10, off = (e & 1023) * 8, dir = seq & 1, bh = seq >> 1;
;         const float* vb = vec + (size_t)bh * S_;
;         const size_t base = (size_t)seq * 8 * 8192 + off;
;         u32x4 sv[8]; float dec[8];
; #pragma unroll
;         for (int i = 0; i < 8; ++i) { const int qb = dir ? 7 - i : i; sv[i] = *(const u32x4*)(Sst + base + (size_t)qb * 8192);
;             const int L0 = qb * 256, L1 = L0 + 255;
;             if (dir == 0) dec[i] = ex2(vb[L1] - (qb ? vb[L0 - 1] : 0.f)); else dec[i] = ex2(vb[VS + L0] - (qb < 7 ? vb[VS + L1 + 1] : 0.f)); }
;         float h[8];
; #pragma unroll
;         for (int k = 0; k < 8; ++k) h[k] = 0.f;
; #pragma unroll
;         for (int i = 0; i < 8; ++i) { const int qb = dir ? 7 - i : i;
;             u32x4 o; o.x = pk2(h[0], h[1]); o.y = pk2(h[2], h[3]); o.z = pk2(h[4], h[5]); o.w = pk2(h[6], h[7]);
;             *(u32x4*)(Hst + base + (size_t)qb * 8192) = o;
;             const u32x4 v = sv[i]; const float d = dec[i];
;             h[0] = h[0] * d + bflo(v.x); h[1] = h[1] * d + bfhi(v.x); h[2] = h[2] * d + bflo(v.y); h[3] = h[3] * d + bfhi(v.y);
;             h[4] = h[4] * d + bflo(v.z); h[5] = h[5] * d + bfhi(v.z); h[6] = h[6] * d + bflo(v.w); h[7] = h[7] * d + bfhi(v.w); }
;     }
.LBB0_556:
	v_ashrrev_i32_e32 v2, 11, v33
	v_ashrrev_i32_e32 v3, 31, v2
	v_lshlrev_b64 v[2:3], 13, v[2:3]
	v_lshl_add_u64 v[18:19], s[18:19], 0, v[2:3]
	v_and_b32_e32 v2, 0x400, v33
	v_cmp_eq_u32_e32 vcc, 0, v2
	v_mov_b32_e32 v39, v17
	v_mov_b32_e32 v59, v17
	v_cndmask_b32_e64 v38, 4, 3, vcc
	v_cndmask_b32_e64 v58, 2, 5, vcc
	v_lshlrev_b32_e32 v34, 14, v38
	v_lshlrev_b32_e32 v38, 10, v38
	v_lshlrev_b32_e32 v64, 14, v58
	v_lshlrev_b32_e32 v58, 10, v58
	v_cndmask_b32_e32 v22, v41, v42, vcc
	v_mov_b32_e32 v23, v17
	v_cndmask_b32_e64 v31, 0, -1, vcc
	v_cndmask_b32_e64 v30, v43, -4, vcc
	v_lshl_add_u64 v[38:39], v[18:19], 0, v[38:39]
	v_lshl_add_u64 v[58:59], v[18:19], 0, v[58:59]
	v_lshl_add_u64 v[50:51], v[38:39], 0, v[22:23]
	v_lshl_add_u64 v[38:39], v[38:39], 0, v[30:31]
	v_lshl_add_u64 v[60:61], v[58:59], 0, v[22:23]
	v_lshl_add_u64 v[58:59], v[58:59], 0, v[30:31]
	global_load_dword v40, v[50:51], off
	v_ashrrev_i32_e32 v0, 10, v33
	global_load_dword v58, v[58:59], off
	v_ashrrev_i32_e32 v1, 31, v0
	global_load_dword v38, v[38:39], off
	v_and_b32_e32 v4, 0x1ff8, v37
	v_bfe_i32 v3, v33, 10, 1
	v_lshlrev_b64 v[20:21], 17, v[0:1]
	v_lshl_or_b32 v20, v4, 1, v20
	v_and_b32_e32 v4, 7, v3
	v_lshlrev_b32_e32 v16, 14, v4
	v_lshlrev_b32_e32 v4, 10, v4
	v_mov_b32_e32 v5, v17
	v_lshl_add_u64 v[4:5], v[18:19], 0, v[4:5]
	v_lshl_add_u64 v[4:5], v[4:5], 0, v[22:23]
	global_load_dword v4, v[4:5], off
	v_cndmask_b32_e64 v8, 6, 1, vcc
	v_cndmask_b32_e64 v12, 5, 2, vcc
	v_cndmask_b32_e64 v54, 3, 4, vcc
	v_cndmask_b32_e64 v63, 1, 6, vcc
	v_lshlrev_b32_e32 v26, 14, v8
	v_lshlrev_b32_e32 v8, 10, v8
	v_mov_b32_e32 v9, v17
	v_lshlrev_b32_e32 v28, 14, v12
	v_lshlrev_b32_e32 v12, 10, v12
	v_mov_b32_e32 v13, v17
	v_mov_b32_e32 v55, v17
	v_lshlrev_b32_e32 v70, 10, v63
	v_mov_b32_e32 v71, v17
	v_lshl_add_u64 v[8:9], v[18:19], 0, v[8:9]
	v_lshl_add_u64 v[12:13], v[18:19], 0, v[12:13]
	v_lshl_add_u64 v[10:11], v[8:9], 0, v[22:23]
	v_lshl_add_u64 v[8:9], v[8:9], 0, v[30:31]
	v_lshl_add_u64 v[14:15], v[12:13], 0, v[22:23]
	v_lshl_add_u64 v[12:13], v[12:13], 0, v[30:31]
	global_load_dword v10, v[10:11], off
	v_lshl_add_u64 v[24:25], s[78:79], 0, v[20:21]
	global_load_dword v14, v[14:15], off
	v_lshl_add_u64 v[0:1], v[24:25], 0, v[16:17]
	global_load_dwordx4 v[0:3], v[0:1], off nt
	v_mov_b32_e32 v27, v17
	v_mov_b32_e32 v29, v17
	v_mov_b32_e32 v35, v17
	v_mov_b32_e32 v39, v17
	v_mov_b32_e32 v65, v17
	v_lshlrev_b32_e32 v68, 14, v63
	v_mov_b32_e32 v69, v17
	v_lshl_add_u64 v[20:21], s[42:43], 0, v[20:21]
	global_load_dword v60, v[60:61], off
	s_waitcnt vmcnt(5)
	v_sub_f32_e32 v38, v40, v38
	v_exp_f32_e32 v40, v38
	v_lshlrev_b32_e32 v38, 14, v54
	v_lshlrev_b32_e32 v54, 10, v54
	v_lshl_add_u64 v[54:55], v[18:19], 0, v[54:55]
	v_lshl_add_u64 v[18:19], v[18:19], 0, v[70:71]
	v_lshl_add_u64 v[56:57], v[54:55], 0, v[22:23]
	v_lshl_add_u64 v[22:23], v[18:19], 0, v[22:23]
	v_lshl_add_u64 v[18:19], v[18:19], 0, v[30:31]
	global_load_dword v22, v[22:23], off
	v_lshl_add_u64 v[54:55], v[54:55], 0, v[30:31]
	global_load_dword v18, v[18:19], off
	v_lshl_add_u64 v[50:51], v[24:25], 0, v[38:39]
	global_load_dword v12, v[12:13], off
	s_waitcnt vmcnt(3)
	v_sub_f32_e32 v58, v60, v58
	global_load_dword v8, v[8:9], off
	v_exp_f32_e32 v45, v4
	global_load_dword v56, v[56:57], off
	v_lshl_add_u64 v[4:5], v[24:25], 0, v[26:27]
	global_load_dword v54, v[54:55], off
	v_lshl_add_u64 v[26:27], v[20:21], 0, v[26:27]
	global_load_dwordx4 v[4:7], v[4:5], off nt
	v_exp_f32_e32 v66, v58
	global_load_dwordx4 v[50:53], v[50:51], off nt
	s_waitcnt vmcnt(6)
	v_sub_f32_e32 v18, v22, v18
	v_lshl_add_u64 v[22:23], v[20:21], 0, v[16:17]
	s_waitcnt vmcnt(5)
	v_sub_f32_e32 v12, v14, v12
	v_exp_f32_e32 v36, v12
	v_lshl_add_u64 v[12:13], v[24:25], 0, v[34:35]
	global_load_dwordx4 v[12:15], v[12:13], off nt
	v_mul_f32_e32 v16, 0, v45
	global_store_dwordx4 v[22:23], v[46:49], off sc0 sc1
	v_lshlrev_b32_e32 v22, 16, v0
	v_and_b32_e32 v23, 0xffff0000, v0
	v_lshlrev_b32_e32 v0, 16, v1
	v_and_b32_e32 v1, 0xffff0000, v1
	v_pk_add_f32 v[30:31], v[16:17], v[0:1] op_sel_hi:[0,1]
	v_lshlrev_b32_e32 v0, 16, v2
	v_and_b32_e32 v1, 0xffff0000, v2
	v_pk_add_f32 v[70:71], v[16:17], v[0:1] op_sel_hi:[0,1]
	v_lshlrev_b32_e32 v0, 16, v3
	v_and_b32_e32 v1, 0xffff0000, v3
	v_pk_add_f32 v[22:23], v[16:17], v[22:23] op_sel_hi:[0,1]
	v_pk_add_f32 v[72:73], v[16:17], v[0:1] op_sel_hi:[0,1]
	v_cvt_pk_bf16_f32 v0, v22, v23
	v_cvt_pk_bf16_f32 v1, v30, v31
	v_cvt_pk_bf16_f32 v2, v70, v71
	v_cvt_pk_bf16_f32 v3, v72, v73
	global_store_dwordx4 v[26:27], v[0:3], off sc0 sc1
	v_exp_f32_e32 v18, v18
	s_waitcnt vmcnt(7)
	v_sub_f32_e32 v8, v10, v8
	v_exp_f32_e32 v32, v8
	v_lshl_add_u64 v[8:9], v[24:25], 0, v[28:29]
	global_load_dwordx4 v[8:11], v[8:9], off nt
	s_waitcnt vmcnt(6)
	v_sub_f32_e32 v54, v56, v54
	v_exp_f32_e32 v62, v54
	v_lshl_add_u64 v[54:55], v[24:25], 0, v[64:65]
	global_load_dwordx4 v[54:57], v[54:55], off nt
	v_lshl_add_u64 v[24:25], v[24:25], 0, v[68:69]
	global_load_dwordx4 v[58:61], v[24:25], off nt
	s_waitcnt vmcnt(7)
; __device__ __forceinline__ unsigned pk2(float lo, float hi) { f32x2 v = {lo, hi}; bf16x2_t b = __builtin_convertvector(v, bf16x2_t); return __builtin_bit_cast(unsigned, b); }
; __device__ __forceinline__ void ssd_state_scan(const Args& a) {
;     ...
;         for (int i = 0; i < 8; ++i) { const int qb = dir ? 7 - i : i;
;             u32x4 o; o.x = pk2(h[0], h[1]); o.y = pk2(h[2], h[3]); o.z = pk2(h[4], h[5]); o.w = pk2(h[6], h[7]);
;             *(u32x4*)(Hst + base + (size_t)qb * 8192) = o;
;             const u32x4 v = sv[i]; const float d = dec[i];
;             h[0] = h[0] * d + bflo(v.x); h[1] = h[1] * d + bfhi(v.x); h[2] = h[2] * d + bflo(v.y); h[3] = h[3] * d + bfhi(v.y);
;             h[4] = h[4] * d + bflo(v.z); h[5] = h[5] * d + bfhi(v.z); h[6] = h[6] * d + bflo(v.w); h[7] = h[7] * d + bfhi(v.w); }
	v_lshlrev_b32_e32 v0, 16, v4
	v_and_b32_e32 v1, 0xffff0000, v4
	v_pk_fma_f32 v[22:23], v[22:23], v[32:33], v[0:1] op_sel_hi:[1,0,1]
	v_lshlrev_b32_e32 v0, 16, v5
	v_and_b32_e32 v1, 0xffff0000, v5
	v_pk_fma_f32 v[4:5], v[30:31], v[32:33], v[0:1] op_sel_hi:[1,0,1]
	v_lshlrev_b32_e32 v0, 16, v6
	v_and_b32_e32 v1, 0xffff0000, v6
	v_pk_fma_f32 v[26:27], v[70:71], v[32:33], v[0:1] op_sel_hi:[1,0,1]
	v_lshlrev_b32_e32 v0, 16, v7
	v_and_b32_e32 v1, 0xffff0000, v7
	v_pk_fma_f32 v[6:7], v[72:73], v[32:33], v[0:1] op_sel_hi:[1,0,1]
	v_cvt_pk_bf16_f32 v0, v22, v23
	v_cvt_pk_bf16_f32 v1, v4, v5
	v_cvt_pk_bf16_f32 v2, v26, v27
	v_cvt_pk_bf16_f32 v3, v6, v7
	v_lshl_add_u64 v[28:29], v[20:21], 0, v[28:29]
	global_store_dwordx4 v[28:29], v[0:3], off sc0 sc1
	v_add_u32_e32 v33, s33, v33
	v_cndmask_b32_e32 v24, 0, v44, vcc
	v_mov_b32_e32 v25, v17
	v_cmp_lt_i32_e32 vcc, s25, v33
	s_or_b64 s[22:23], vcc, s[22:23]
	s_waitcnt vmcnt(3)
	v_lshlrev_b32_e32 v0, 16, v8
	v_and_b32_e32 v1, 0xffff0000, v8
	v_pk_fma_f32 v[22:23], v[22:23], v[36:37], v[0:1] op_sel_hi:[1,0,1]
	v_lshlrev_b32_e32 v0, 16, v9
	v_and_b32_e32 v1, 0xffff0000, v9
	v_pk_fma_f32 v[4:5], v[4:5], v[36:37], v[0:1] op_sel_hi:[1,0,1]
	v_lshlrev_b32_e32 v0, 16, v10
	v_and_b32_e32 v1, 0xffff0000, v10
	v_pk_fma_f32 v[8:9], v[26:27], v[36:37], v[0:1] op_sel_hi:[1,0,1]
	v_lshlrev_b32_e32 v0, 16, v11
	v_and_b32_e32 v1, 0xffff0000, v11
	v_pk_fma_f32 v[6:7], v[6:7], v[36:37], v[0:1] op_sel_hi:[1,0,1]
	v_cvt_pk_bf16_f32 v0, v22, v23
	v_cvt_pk_bf16_f32 v1, v4, v5
	v_cvt_pk_bf16_f32 v2, v8, v9
	v_cvt_pk_bf16_f32 v3, v6, v7
	v_lshl_add_u64 v[10:11], v[20:21], 0, v[34:35]
	global_store_dwordx4 v[10:11], v[0:3], off sc0 sc1
	v_add_u32_e32 v37, s24, v37
	s_nop 0
	v_lshlrev_b32_e32 v0, 16, v12
	v_and_b32_e32 v1, 0xffff0000, v12
	v_pk_fma_f32 v[10:11], v[22:23], v[40:41], v[0:1] op_sel_hi:[1,0,1]
	v_lshlrev_b32_e32 v0, 16, v13
	v_and_b32_e32 v1, 0xffff0000, v13
	v_pk_fma_f32 v[4:5], v[4:5], v[40:41], v[0:1] op_sel_hi:[1,0,1]
	v_lshlrev_b32_e32 v0, 16, v14
	v_and_b32_e32 v1, 0xffff0000, v14
	v_pk_fma_f32 v[8:9], v[8:9], v[40:41], v[0:1] op_sel_hi:[1,0,1]
	v_lshlrev_b32_e32 v0, 16, v15
	v_and_b32_e32 v1, 0xffff0000, v15
	v_pk_fma_f32 v[6:7], v[6:7], v[40:41], v[0:1] op_sel_hi:[1,0,1]
	v_cvt_pk_bf16_f32 v0, v10, v11
	v_cvt_pk_bf16_f32 v1, v4, v5
	v_cvt_pk_bf16_f32 v2, v8, v9
	v_cvt_pk_bf16_f32 v3, v6, v7
	v_lshl_add_u64 v[12:13], v[20:21], 0, v[38:39]
	global_store_dwordx4 v[12:13], v[0:3], off sc0 sc1
	v_lshl_add_u64 v[12:13], v[20:21], 0, v[64:65]
	s_nop 0
	v_lshlrev_b32_e32 v0, 16, v50
	v_and_b32_e32 v1, 0xffff0000, v50
	v_pk_fma_f32 v[10:11], v[10:11], v[62:63], v[0:1] op_sel_hi:[1,0,1]
	v_lshlrev_b32_e32 v0, 16, v51
	v_and_b32_e32 v1, 0xffff0000, v51
	v_pk_fma_f32 v[4:5], v[4:5], v[62:63], v[0:1] op_sel_hi:[1,0,1]
	v_lshlrev_b32_e32 v0, 16, v52
	v_and_b32_e32 v1, 0xffff0000, v52
	v_pk_fma_f32 v[8:9], v[8:9], v[62:63], v[0:1] op_sel_hi:[1,0,1]
	v_lshlrev_b32_e32 v0, 16, v53
	v_and_b32_e32 v1, 0xffff0000, v53
	v_pk_fma_f32 v[6:7], v[6:7], v[62:63], v[0:1] op_sel_hi:[1,0,1]
	v_cvt_pk_bf16_f32 v0, v10, v11
	v_cvt_pk_bf16_f32 v1, v4, v5
	v_cvt_pk_bf16_f32 v2, v8, v9
	v_cvt_pk_bf16_f32 v3, v6, v7
	global_store_dwordx4 v[12:13], v[0:3], off sc0 sc1
	v_lshl_add_u64 v[12:13], v[20:21], 0, v[68:69]
	s_waitcnt vmcnt(5)
	v_lshlrev_b32_e32 v0, 16, v54
	v_and_b32_e32 v1, 0xffff0000, v54
	v_pk_fma_f32 v[10:11], v[10:11], v[66:67], v[0:1] op_sel_hi:[1,0,1]
	v_lshlrev_b32_e32 v0, 16, v55
	v_and_b32_e32 v1, 0xffff0000, v55
	v_pk_fma_f32 v[4:5], v[4:5], v[66:67], v[0:1] op_sel_hi:[1,0,1]
	v_lshlrev_b32_e32 v0, 16, v56
	v_and_b32_e32 v1, 0xffff0000, v56
	v_pk_fma_f32 v[8:9], v[8:9], v[66:67], v[0:1] op_sel_hi:[1,0,1]
	v_lshlrev_b32_e32 v0, 16, v57
	v_and_b32_e32 v1, 0xffff0000, v57
	v_pk_fma_f32 v[6:7], v[6:7], v[66:67], v[0:1] op_sel_hi:[1,0,1]
	v_cvt_pk_bf16_f32 v0, v10, v11
	v_cvt_pk_bf16_f32 v1, v4, v5
	v_cvt_pk_bf16_f32 v2, v8, v9
	v_cvt_pk_bf16_f32 v3, v6, v7
	global_store_dwordx4 v[12:13], v[0:3], off sc0 sc1
	s_waitcnt vmcnt(5)
	s_nop 0
	v_lshlrev_b32_e32 v2, 16, v59
	v_and_b32_e32 v3, 0xffff0000, v59
	v_pk_fma_f32 v[2:3], v[4:5], v[18:19], v[2:3] op_sel_hi:[1,0,1]
	v_lshlrev_b32_e32 v4, 16, v60
	v_and_b32_e32 v5, 0xffff0000, v60
	v_lshlrev_b32_e32 v0, 16, v58
	v_and_b32_e32 v1, 0xffff0000, v58
	v_pk_fma_f32 v[4:5], v[8:9], v[18:19], v[4:5] op_sel_hi:[1,0,1]
	v_lshlrev_b32_e32 v8, 16, v61
	v_and_b32_e32 v9, 0xffff0000, v61
	v_pk_fma_f32 v[0:1], v[10:11], v[18:19], v[0:1] op_sel_hi:[1,0,1]
	v_pk_fma_f32 v[6:7], v[6:7], v[18:19], v[8:9] op_sel_hi:[1,0,1]
	v_cvt_pk_bf16_f32 v0, v0, v1
	v_cvt_pk_bf16_f32 v1, v2, v3
	v_cvt_pk_bf16_f32 v2, v4, v5
	v_cvt_pk_bf16_f32 v3, v6, v7
	v_lshl_add_u64 v[4:5], v[20:21], 0, v[24:25]
	global_store_dwordx4 v[4:5], v[0:3], off sc0 sc1
	s_andn2_b64 exec, exec, s[22:23]
	s_cbranch_execnz .LBB0_556

; #define PG8_LAS __attribute__((address_space(3)))
; __device__ __forceinline__ unsigned cvt_pk_bf16(float lo, float hi) { unsigned r; asm volatile("v_cvt_pk_bf16_f32 %0, %1, %2" : "=v"(r) : "v"(lo), "v"(hi)); return r; }
; #pragma unroll
;         for (int i = 1; i < 4; ++i) if (pms[i] == u.pm) sl = i;
;         return sl; }
;     __device__ __forceinline__ void operator()(const f32x4 (&acc)[2][2][4][2], const Unit& u, int wr, int wc, int fr, int fq) const {
;         const int row0 = u.pm * BM + wr * 64 + fr; const int col0 = u.pn * BM + wc * 32 + 8 * fq;
;         const PG8_LAS float* f = fac + slot_of(u) * 768 + 512 + wr * 64 + fr;
; #pragma unroll
;         for (int ai = 0; ai < 2; ++ai) {
;             f32x4 b0[4][2], b1[4][2]; float fs[4];
; #pragma unroll
;             for (int m = 0; m < 4; ++m) { fs[m] = f[ai * HALF + m * 16];
; #pragma unroll
;                 for (int bj = 0; bj < 2; ++bj) { const size_t o = (size_t)(row0 + ai * HALF + m * 16) * ldc + col0 + bj * HALF; b0[m][bj] = *(const f32x4*)(base + o); b1[m][bj] = *(const f32x4*)(base + o + 4); } }
; #pragma unroll
;             for (int m = 0; m < 4; ++m) { const int row = row0 + ai * HALF + m * 16; const size_t ro = (size_t)row * ldc + col0; float sq = 0.f;
; #pragma unroll
;                 for (int bj = 0; bj < 2; ++bj) { const size_t o = ro + bj * HALF;
;                     const f32x4 v0 = b0[m][bj] + acc[ai][bj][m][0] * fs[m], v1 = b1[m][bj] + acc[ai][bj][m][1] * fs[m];
;                     u32x4 w; w.x = cvt_pk_bf16(v0[0], v0[1]); w.y = cvt_pk_bf16(v0[2], v0[3]); w.z = cvt_pk_bf16(v1[0], v1[1]); w.w = cvt_pk_bf16(v1[2], v1[3]); *(u32x4*)(xb + o) = w;
;                     sq += (v0[0] * v0[0] + v0[1] * v0[1]) + (v0[2] * v0[2] + v0[3] * v0[3]) + (v1[0] * v1[0] + v1[1] * v1[1]) + (v1[2] * v1[2] + v1[3] * v1[3]); }
;                 sq += __shfl_xor(sq, 16); sq += __shfl_xor(sq, 32); if (fq == 0) atomicAdd(ssq + row, sq); }
.LBB0_745:
	v_mov_b32_e32 v1, s79
	ds_read2_b32 v[132:133], v1 offset1:1
	v_mov_b32_e32 v1, s80
	ds_read_b32 v1, v1
	v_lshl_add_u32 v196, s60, 8, v212
	s_waitcnt lgkmcnt(0)
	v_lshl_or_b32 v2, s84, 8, v214
	s_waitcnt lgkmcnt(0)
	v_cmp_eq_u32_e32 vcc, s60, v132
	v_ashrrev_i32_e32 v197, 31, v196
	v_or_b32_e32 v206, 16, v196
	v_cndmask_b32_e32 v3, 0, v218, vcc
	v_cmp_ne_u32_e32 vcc, s60, v133
	v_lshlrev_b64 v[132:133], 12, v[196:197]
	v_ashrrev_i32_e32 v207, 31, v206
	v_cndmask_b32_e32 v3, v219, v3, vcc
	v_cmp_ne_u32_e32 vcc, s60, v1
	v_or_b32_e32 v204, 32, v196
	v_ashrrev_i32_e32 v205, 31, v204
	v_cndmask_b32_e32 v1, v220, v3, vcc
	v_ashrrev_i32_e32 v3, 31, v2
	v_add_u32_e32 v1, v215, v1
	v_lshl_add_u64 v[198:199], v[2:3], 2, s[8:9]
	v_add_u32_e32 v221, 0x800, v1
	v_lshl_add_u64 v[132:133], v[198:199], 0, v[132:133]
	ds_read2_b32 v[208:209], v221 offset1:16
	global_load_dwordx4 v[222:225], v[132:133], off offset:16 nt
	global_load_dwordx4 v[226:229], v[132:133], off nt
	global_load_dwordx4 v[230:233], v[132:133], off offset:528 nt
	global_load_dwordx4 v[234:237], v[132:133], off offset:512 nt
	v_lshlrev_b64 v[132:133], 12, v[206:207]
	v_lshl_add_u64 v[132:133], v[198:199], 0, v[132:133]
	global_load_dwordx4 v[172:175], v[132:133], off offset:16 nt
	global_load_dwordx4 v[176:179], v[132:133], off nt
	global_load_dwordx4 v[164:167], v[132:133], off offset:528 nt
	global_load_dwordx4 v[168:171], v[132:133], off offset:512 nt
	v_lshlrev_b64 v[132:133], 12, v[204:205]
	v_or_b32_e32 v200, 48, v196
	v_lshl_add_u64 v[132:133], v[198:199], 0, v[132:133]
	v_ashrrev_i32_e32 v201, 31, v200
	ds_read2_b32 v[202:203], v221 offset0:32 offset1:48
	global_load_dwordx4 v[156:159], v[132:133], off offset:16 nt
	global_load_dwordx4 v[160:163], v[132:133], off nt
	global_load_dwordx4 v[144:147], v[132:133], off offset:528 nt
	global_load_dwordx4 v[152:155], v[132:133], off offset:512 nt
	v_lshlrev_b64 v[132:133], 12, v[200:201]
	v_lshl_add_u64 v[136:137], v[198:199], 0, v[132:133]
	global_load_dwordx4 v[140:143], v[136:137], off offset:16 nt
	global_load_dwordx4 v[148:151], v[136:137], off nt
	global_load_dwordx4 v[132:135], v[136:137], off offset:528 nt
	s_nop 0
	global_load_dwordx4 v[136:139], v[136:137], off offset:512 nt
	s_waitcnt vmcnt(0) lgkmcnt(0)
	v_pk_fma_f32 v[124:125], v[124:125], v[208:209], v[222:223] op_sel_hi:[1,0,1]
	v_lshlrev_b64 v[222:223], 11, v[196:197]
	v_lshl_add_u64 v[222:223], s[48:49], 0, v[222:223]
	v_pk_fma_f32 v[228:229], v[118:119], v[208:209], v[228:229] op_sel_hi:[1,0,1]
	v_pk_fma_f32 v[226:227], v[116:117], v[208:209], v[226:227] op_sel_hi:[1,0,1]
	v_lshl_add_u64 v[222:223], v[2:3], 1, v[222:223]
	v_cvt_pk_bf16_f32 v116, v226, v227
	v_pk_fma_f32 v[126:127], v[126:127], v[208:209], v[224:225] op_sel_hi:[1,0,1]
	v_cvt_pk_bf16_f32 v117, v228, v229
	v_cvt_pk_bf16_f32 v118, v124, v125
	v_mul_f32_e32 v1, v227, v227
	v_cvt_pk_bf16_f32 v119, v126, v127
	global_store_dwordx4 v[222:223], v[116:119], off
	v_fmac_f32_e32 v1, v226, v226
	v_pk_fma_f32 v[122:123], v[122:123], v[208:209], v[236:237] op_sel_hi:[1,0,1]
	v_mul_f32_e32 v116, v229, v229
	v_fmac_f32_e32 v116, v228, v228
	v_add_f32_e32 v1, v1, v116
	v_mul_f32_e32 v116, v125, v125
	v_fmac_f32_e32 v116, v124, v124
	v_add_f32_e32 v1, v116, v1
	v_mul_f32_e32 v116, v127, v127
	v_fmac_f32_e32 v116, v126, v126
	v_add_f32_e32 v1, v116, v1
	v_pk_fma_f32 v[120:121], v[120:121], v[208:209], v[234:235] op_sel_hi:[1,0,1]
	v_pk_fma_f32 v[124:125], v[130:131], v[208:209], v[232:233] op_sel_hi:[1,0,1]
	v_cvt_pk_bf16_f32 v116, v120, v121
	v_cvt_pk_bf16_f32 v117, v122, v123
	v_pk_fma_f32 v[126:127], v[128:129], v[208:209], v[230:231] op_sel_hi:[1,0,1]
	s_nop 0
	v_cvt_pk_bf16_f32 v118, v126, v127
	v_cvt_pk_bf16_f32 v119, v124, v125
	global_store_dwordx4 v[222:223], v[116:119], off offset:256
	s_nop 1
	v_mul_f32_e32 v116, v121, v121
	v_mul_f32_e32 v117, v123, v123
	v_fmac_f32_e32 v116, v120, v120
	v_fmac_f32_e32 v117, v122, v122
	v_add_f32_e32 v116, v116, v117
	v_mul_f32_e32 v117, v127, v127
	v_fmac_f32_e32 v117, v126, v126
	v_add_f32_e32 v116, v116, v117
	v_mul_f32_e32 v117, v125, v125
	v_fmac_f32_e32 v117, v124, v124
	v_add_f32_e32 v116, v117, v116
	v_and_b32_e32 v117, 64, v217
	v_add_f32_e32 v116, v1, v116
	v_xor_b32_e32 v1, 16, v217
	v_add_u32_e32 v117, 64, v117
	v_cmp_lt_i32_e32 vcc, v1, v117
	s_nop 1
	v_cndmask_b32_e32 v1, v217, v1, vcc
	v_lshlrev_b32_e32 v1, 2, v1
	ds_bpermute_b32 v118, v1, v116
	s_waitcnt lgkmcnt(0)
	v_add_f32_e32 v116, v116, v118
	v_xor_b32_e32 v118, 32, v217
	v_cmp_lt_i32_e32 vcc, v118, v117
	s_nop 1
	v_cndmask_b32_e32 v117, v217, v118, vcc
	v_lshlrev_b32_e32 v208, 2, v117
	ds_bpermute_b32 v117, v208, v116
	s_and_saveexec_b64 s[24:25], s[40:41]
	s_cbranch_execz .LBB0_747
	v_lshl_add_u64 v[118:119], v[196:197], 2, s[12:13]
	s_waitcnt lgkmcnt(0)
	v_add_f32_e32 v116, v116, v117
	global_atomic_add_f32 v[118:119], v116, off

; __device__ __forceinline__ unsigned cvt_pk_bf16(float lo, float hi) { unsigned r; asm volatile("v_cvt_pk_bf16_f32 %0, %1, %2" : "=v"(r) : "v"(lo), "v"(hi)); return r; }
;     __device__ __forceinline__ void operator()(const f32x4 (&acc)[2][2][4][2], const Unit& u, int wr, int wc, int fr, int fq) const {
;     ...
;                 for (int bj = 0; bj < 2; ++bj) { const size_t o = (size_t)(row0 + ai * HALF + m * 16) * ldc + col0 + bj * HALF;
;                     if (STATS) { b0[m][bj] = *(const f32x4*)(base + o); b1[m][bj] = *(const f32x4*)(base + o + 4); } else wx[m][bj] = *(const u32x4*)(xb + o); }
; #pragma unroll
;             for (int m = 0; m < 4; ++m) { const int row = row0 + ai * HALF + m * 16; const size_t ro = (size_t)row * ldc + col0; float sq = 0.f;
; #pragma unroll
;                 for (int bj = 0; bj < 2; ++bj) { const size_t o = ro + bj * HALF;
;                     if (STATS) {
;                         const f32x4 v0 = b0[m][bj] + acc[ai][bj][m][0], v1 = b1[m][bj] + acc[ai][bj][m][1];
;                         u32x4 w; w.x = cvt_pk_bf16(v0[0], v0[1]); w.y = cvt_pk_bf16(v0[2], v0[3]); w.z = cvt_pk_bf16(v1[0], v1[1]); w.w = cvt_pk_bf16(v1[2], v1[3]); *(u32x4*)(xb + o) = w;
;                         sq += (v0[0] * v0[0] + v0[1] * v0[1]) + (v0[2] * v0[2] + v0[3] * v0[3]) + (v1[0] * v1[0] + v1[1] * v1[1]) + (v1[2] * v1[2] + v1[3] * v1[3]);
;                     } else {
;                         const u32x4 w = wx[m][bj];
;                         f32x4 c0, c1; c0[0] = __builtin_bit_cast(float, w.x << 16); c0[1] = __builtin_bit_cast(float, w.x & 0xffff0000u); c0[2] = __builtin_bit_cast(float, w.y << 16); c0[3] = __builtin_bit_cast(float, w.y & 0xffff0000u);
;                         c1[0] = __builtin_bit_cast(float, w.z << 16); c1[1] = __builtin_bit_cast(float, w.z & 0xffff0000u); c1[2] = __builtin_bit_cast(float, w.w << 16); c1[3] = __builtin_bit_cast(float, w.w & 0xffff0000u);
;                         *(f32x4*)(out + o) = c0 + acc[ai][bj][m][0]; *(f32x4*)(out + o + 4) = c1 + acc[ai][bj][m][1];
.LBB0_915:
	v_lshl_add_u32 v148, s26, 8, v152
	v_lshl_or_b32 v144, s45, 8, v154
	v_ashrrev_i32_e32 v145, 31, v144
	v_ashrrev_i32_e32 v149, 31, v148
	v_lshl_add_u64 v[146:147], v[144:145], 1, s[48:49]
	v_lshlrev_b64 v[150:151], 11, v[148:149]
	v_or_b32_e32 v178, 16, v148
	v_lshl_add_u64 v[150:151], v[146:147], 0, v[150:151]
	v_ashrrev_i32_e32 v179, 31, v178
	global_load_dwordx4 v[158:161], v[150:151], off nt
	global_load_dwordx4 v[162:165], v[150:151], off offset:256 nt
	v_lshlrev_b64 v[150:151], 11, v[178:179]
	v_or_b32_e32 v190, 32, v148
	v_lshl_add_u64 v[150:151], v[146:147], 0, v[150:151]
	v_ashrrev_i32_e32 v191, 31, v190
	global_load_dwordx4 v[166:169], v[150:151], off nt
	global_load_dwordx4 v[170:173], v[150:151], off offset:256 nt
	v_lshlrev_b64 v[150:151], 11, v[190:191]
	v_lshl_add_u64 v[180:181], v[146:147], 0, v[150:151]
	global_load_dwordx4 v[174:177], v[180:181], off nt
	v_or_b32_e32 v150, 48, v148
	v_ashrrev_i32_e32 v151, 31, v150
	v_lshlrev_b64 v[186:187], 12, v[178:179]
	global_load_dwordx4 v[178:181], v[180:181], off offset:256 nt
	v_lshlrev_b64 v[182:183], 12, v[148:149]
	v_lshlrev_b64 v[184:185], 11, v[150:151]
	v_lshlrev_b64 v[144:145], 2, v[144:145]
	v_lshl_add_u64 v[182:183], s[54:55], 0, v[182:183]
	v_lshl_add_u64 v[188:189], v[146:147], 0, v[184:185]
	v_lshl_add_u64 v[192:193], v[182:183], 0, v[144:145]
	v_lshl_add_u64 v[194:195], s[54:55], 0, v[186:187]
	global_load_dwordx4 v[182:185], v[188:189], off nt
	s_nop 0
	global_load_dwordx4 v[186:189], v[188:189], off offset:256 nt
	v_lshl_add_u64 v[194:195], v[194:195], 0, v[144:145]
	s_and_b64 vcc, exec, s[4:5]
	s_mov_b64 s[4:5], -1
	s_waitcnt vmcnt(0)
	v_lshlrev_b32_e32 v196, 16, v158
	v_and_b32_e32 v197, 0xffff0000, v158
	v_lshlrev_b32_e32 v158, 16, v159
	v_and_b32_e32 v159, 0xffff0000, v159
	v_lshlrev_b32_e32 v198, 16, v160
	v_and_b32_e32 v199, 0xffff0000, v160
	v_lshlrev_b32_e32 v160, 16, v161
	v_and_b32_e32 v161, 0xffff0000, v161
	v_lshlrev_b32_e32 v200, 16, v162
	v_and_b32_e32 v201, 0xffff0000, v162
	v_lshlrev_b32_e32 v162, 16, v163
	v_and_b32_e32 v163, 0xffff0000, v163
	v_lshlrev_b32_e32 v202, 16, v164
	v_and_b32_e32 v203, 0xffff0000, v164
	v_lshlrev_b32_e32 v164, 16, v165
	v_and_b32_e32 v165, 0xffff0000, v165
	v_pk_add_f32 v[126:127], v[126:127], v[158:159]
	v_pk_add_f32 v[122:123], v[122:123], v[160:161]
	v_pk_add_f32 v[118:119], v[118:119], v[162:163]
	v_pk_add_f32 v[114:115], v[114:115], v[164:165]
	v_lshlrev_b32_e32 v158, 16, v166
	v_and_b32_e32 v159, 0xffff0000, v166
	v_lshlrev_b32_e32 v160, 16, v167
	v_and_b32_e32 v161, 0xffff0000, v167
	v_lshlrev_b32_e32 v162, 16, v168
	v_and_b32_e32 v163, 0xffff0000, v168
	v_lshlrev_b32_e32 v164, 16, v169
	v_and_b32_e32 v165, 0xffff0000, v169
	v_lshlrev_b32_e32 v166, 16, v170
	v_and_b32_e32 v167, 0xffff0000, v170
	v_lshlrev_b32_e32 v168, 16, v171
	v_and_b32_e32 v169, 0xffff0000, v171
	v_lshlrev_b32_e32 v170, 16, v172
	v_and_b32_e32 v171, 0xffff0000, v172
	v_lshlrev_b32_e32 v172, 16, v173
	v_and_b32_e32 v173, 0xffff0000, v173
	v_pk_add_f32 v[124:125], v[124:125], v[196:197]
	v_pk_add_f32 v[110:111], v[110:111], v[160:161]
	v_pk_add_f32 v[108:109], v[108:109], v[158:159]
	v_pk_add_f32 v[98:99], v[98:99], v[172:173]
	v_pk_add_f32 v[96:97], v[96:97], v[170:171]
	v_pk_add_f32 v[120:121], v[120:121], v[198:199]
	v_pk_add_f32 v[116:117], v[116:117], v[200:201]
	v_pk_add_f32 v[112:113], v[112:113], v[202:203]
	global_store_dwordx4 v[192:193], v[124:127], off
	global_store_dwordx4 v[192:193], v[120:123], off offset:16
	global_store_dwordx4 v[192:193], v[116:119], off offset:512
	global_store_dwordx4 v[192:193], v[112:115], off offset:528
	v_pk_add_f32 v[106:107], v[106:107], v[164:165]
	v_pk_add_f32 v[104:105], v[104:105], v[162:163]
	v_pk_add_f32 v[102:103], v[102:103], v[168:169]
	v_pk_add_f32 v[100:101], v[100:101], v[166:167]
	global_store_dwordx4 v[194:195], v[108:111], off
	global_store_dwordx4 v[194:195], v[104:107], off offset:16
	global_store_dwordx4 v[194:195], v[100:103], off offset:512
	global_store_dwordx4 v[194:195], v[96:99], off offset:528
	s_nop 0
	v_lshlrev_b32_e32 v100, 16, v176
	v_lshlrev_b32_e32 v96, 16, v174
	v_and_b32_e32 v97, 0xffff0000, v174
	v_pk_add_f32 v[92:93], v[92:93], v[96:97]
	v_lshlrev_b64 v[96:97], 12, v[190:191]
	v_lshlrev_b32_e32 v98, 16, v175
	v_and_b32_e32 v99, 0xffff0000, v175
	v_lshl_add_u64 v[96:97], s[54:55], 0, v[96:97]
	v_pk_add_f32 v[94:95], v[94:95], v[98:99]
	v_lshl_add_u64 v[96:97], v[96:97], 0, v[144:145]
	global_store_dwordx4 v[96:97], v[92:95], off
	v_and_b32_e32 v101, 0xffff0000, v176
	v_lshlrev_b32_e32 v102, 16, v177
	v_lshlrev_b32_e32 v92, 16, v180
	v_and_b32_e32 v93, 0xffff0000, v180
	v_lshlrev_b32_e32 v94, 16, v181
	v_and_b32_e32 v95, 0xffff0000, v181
	v_and_b32_e32 v103, 0xffff0000, v177
	v_pk_add_f32 v[82:83], v[82:83], v[94:95]
	v_pk_add_f32 v[80:81], v[80:81], v[92:93]
	v_pk_add_f32 v[90:91], v[90:91], v[102:103]
	v_pk_add_f32 v[88:89], v[88:89], v[100:101]
	global_store_dwordx4 v[96:97], v[80:83], off offset:528
	global_store_dwordx4 v[96:97], v[88:91], off offset:16
	v_add_u32_e32 v98, 0x80, v148
	v_lshlrev_b32_e32 v80, 16, v182
	v_and_b32_e32 v81, 0xffff0000, v182
	v_lshlrev_b32_e32 v88, 16, v178
	v_and_b32_e32 v89, 0xffff0000, v178
	v_lshlrev_b32_e32 v90, 16, v179
	v_and_b32_e32 v91, 0xffff0000, v179
	v_pk_add_f32 v[76:77], v[76:77], v[80:81]
	v_lshlrev_b64 v[80:81], 12, v[150:151]
	v_pk_add_f32 v[86:87], v[86:87], v[90:91]
	v_pk_add_f32 v[84:85], v[84:85], v[88:89]
	v_lshlrev_b32_e32 v82, 16, v183
	v_and_b32_e32 v83, 0xffff0000, v183
	v_lshl_add_u64 v[80:81], s[54:55], 0, v[80:81]
	global_store_dwordx4 v[96:97], v[84:87], off offset:512
	v_pk_add_f32 v[78:79], v[78:79], v[82:83]
; __device__ __forceinline__ unsigned cvt_pk_bf16(float lo, float hi) { unsigned r; asm volatile("v_cvt_pk_bf16_f32 %0, %1, %2" : "=v"(r) : "v"(lo), "v"(hi)); return r; }
;     __device__ __forceinline__ void operator()(const f32x4 (&acc)[2][2][4][2], const Unit& u, int wr, int wc, int fr, int fq) const {
;     ...
;         for (int ai = 0; ai < 2; ++ai) {
;             f32x4 b0[4][2], b1[4][2]; u32x4 wx[4][2];
; #pragma unroll
;             for (int m = 0; m < 4; ++m)
; #pragma unroll
;                 for (int bj = 0; bj < 2; ++bj) { const size_t o = (size_t)(row0 + ai * HALF + m * 16) * ldc + col0 + bj * HALF;
;                     if (STATS) { b0[m][bj] = *(const f32x4*)(base + o); b1[m][bj] = *(const f32x4*)(base + o + 4); } else wx[m][bj] = *(const u32x4*)(xb + o); }
; #pragma unroll
;             for (int m = 0; m < 4; ++m) { const int row = row0 + ai * HALF + m * 16; const size_t ro = (size_t)row * ldc + col0; float sq = 0.f;
; #pragma unroll
;                 for (int bj = 0; bj < 2; ++bj) { const size_t o = ro + bj * HALF;
;                     if (STATS) {
;                         const f32x4 v0 = b0[m][bj] + acc[ai][bj][m][0], v1 = b1[m][bj] + acc[ai][bj][m][1];
;                         u32x4 w; w.x = cvt_pk_bf16(v0[0], v0[1]); w.y = cvt_pk_bf16(v0[2], v0[3]); w.z = cvt_pk_bf16(v1[0], v1[1]); w.w = cvt_pk_bf16(v1[2], v1[3]); *(u32x4*)(xb + o) = w;
;                         sq += (v0[0] * v0[0] + v0[1] * v0[1]) + (v0[2] * v0[2] + v0[3] * v0[3]) + (v1[0] * v1[0] + v1[1] * v1[1]) + (v1[2] * v1[2] + v1[3] * v1[3]);
;                     } else {
;                         const u32x4 w = wx[m][bj];
;                         f32x4 c0, c1; c0[0] = __builtin_bit_cast(float, w.x << 16); c0[1] = __builtin_bit_cast(float, w.x & 0xffff0000u); c0[2] = __builtin_bit_cast(float, w.y << 16); c0[3] = __builtin_bit_cast(float, w.y & 0xffff0000u);
;                         c1[0] = __builtin_bit_cast(float, w.z << 16); c1[1] = __builtin_bit_cast(float, w.z & 0xffff0000u); c1[2] = __builtin_bit_cast(float, w.w << 16); c1[3] = __builtin_bit_cast(float, w.w & 0xffff0000u);
;                         *(f32x4*)(out + o) = c0 + acc[ai][bj][m][0]; *(f32x4*)(out + o + 4) = c1 + acc[ai][bj][m][1];
	v_lshl_add_u64 v[80:81], v[80:81], 0, v[144:145]
	v_lshlrev_b32_e32 v84, 16, v184
	v_and_b32_e32 v85, 0xffff0000, v184
	v_lshlrev_b32_e32 v86, 16, v185
	v_and_b32_e32 v87, 0xffff0000, v185
	global_store_dwordx4 v[80:81], v[76:79], off
	v_pk_add_f32 v[74:75], v[74:75], v[86:87]
	v_pk_add_f32 v[72:73], v[72:73], v[84:85]
	v_lshlrev_b32_e32 v76, 16, v188
	v_and_b32_e32 v77, 0xffff0000, v188
	v_lshlrev_b32_e32 v78, 16, v189
	v_and_b32_e32 v79, 0xffff0000, v189
	global_store_dwordx4 v[80:81], v[72:75], off offset:16
	v_pk_add_f32 v[66:67], v[66:67], v[78:79]
	v_pk_add_f32 v[64:65], v[64:65], v[76:77]
	v_lshlrev_b32_e32 v72, 16, v186
	v_and_b32_e32 v73, 0xffff0000, v186
	v_lshlrev_b32_e32 v74, 16, v187
	v_and_b32_e32 v75, 0xffff0000, v187
	v_ashrrev_i32_e32 v99, 31, v98
	v_pk_add_f32 v[70:71], v[70:71], v[74:75]
	v_pk_add_f32 v[68:69], v[68:69], v[72:73]
	global_store_dwordx4 v[80:81], v[64:67], off offset:528
	global_store_dwordx4 v[80:81], v[68:71], off offset:512
	v_add_u32_e32 v100, 0x90, v148
	v_lshlrev_b64 v[64:65], 11, v[98:99]
	v_lshl_add_u64 v[64:65], v[146:147], 0, v[64:65]
	global_load_dwordx4 v[70:73], v[64:65], off nt
	global_load_dwordx4 v[74:77], v[64:65], off offset:256 nt
	v_ashrrev_i32_e32 v101, 31, v100
	v_lshlrev_b64 v[64:65], 11, v[100:101]
	v_lshl_add_u64 v[64:65], v[146:147], 0, v[64:65]
	global_load_dwordx4 v[78:81], v[64:65], off nt
	global_load_dwordx4 v[82:85], v[64:65], off offset:256 nt
	v_add_u32_e32 v102, 0xa0, v148
	v_ashrrev_i32_e32 v103, 31, v102
	v_lshlrev_b64 v[64:65], 11, v[102:103]
	v_lshl_add_u64 v[64:65], v[146:147], 0, v[64:65]
	global_load_dwordx4 v[86:89], v[64:65], off nt
	global_load_dwordx4 v[90:93], v[64:65], off offset:256 nt
	v_add_u32_e32 v68, 0xb0, v148
	v_ashrrev_i32_e32 v69, 31, v68
	v_lshlrev_b64 v[64:65], 11, v[68:69]
	v_lshl_add_u64 v[64:65], v[146:147], 0, v[64:65]
	global_load_dwordx4 v[94:97], v[64:65], off nt
	s_nop 0
	global_load_dwordx4 v[64:67], v[64:65], off offset:256 nt
	s_waitcnt vmcnt(0)
	v_lshlrev_b32_e32 v104, 16, v70
	v_and_b32_e32 v105, 0xffff0000, v70
	v_lshlrev_b32_e32 v70, 16, v71
	v_and_b32_e32 v71, 0xffff0000, v71
	v_pk_add_f32 v[62:63], v[62:63], v[70:71]
	v_lshlrev_b64 v[70:71], 12, v[98:99]
	v_lshl_add_u64 v[70:71], s[54:55], 0, v[70:71]
	v_pk_add_f32 v[60:61], v[60:61], v[104:105]
	v_lshl_add_u64 v[70:71], v[70:71], 0, v[144:145]
	global_store_dwordx4 v[70:71], v[60:63], off
	v_lshlrev_b32_e32 v106, 16, v72
	v_and_b32_e32 v107, 0xffff0000, v72
	v_lshlrev_b32_e32 v60, 16, v76
	v_and_b32_e32 v61, 0xffff0000, v76
	v_lshlrev_b32_e32 v62, 16, v77
	v_and_b32_e32 v63, 0xffff0000, v77
	v_pk_add_f32 v[50:51], v[50:51], v[62:63]
	v_pk_add_f32 v[48:49], v[48:49], v[60:61]
	global_store_dwordx4 v[70:71], v[48:51], off offset:528
	v_lshlrev_b32_e32 v72, 16, v73
	v_and_b32_e32 v73, 0xffff0000, v73
	v_lshlrev_b32_e32 v48, 16, v78
	v_and_b32_e32 v49, 0xffff0000, v78
	v_pk_add_f32 v[44:45], v[44:45], v[48:49]
	v_lshlrev_b64 v[48:49], 12, v[100:101]
	v_lshlrev_b32_e32 v50, 16, v79
	v_and_b32_e32 v51, 0xffff0000, v79
	v_lshl_add_u64 v[48:49], s[54:55], 0, v[48:49]
	v_pk_add_f32 v[58:59], v[58:59], v[72:73]
	v_pk_add_f32 v[56:57], v[56:57], v[106:107]
	v_pk_add_f32 v[46:47], v[46:47], v[50:51]
	v_lshl_add_u64 v[48:49], v[48:49], 0, v[144:145]
	global_store_dwordx4 v[70:71], v[56:59], off offset:16
	global_store_dwordx4 v[48:49], v[44:47], off
	s_nop 0
	v_lshlrev_b32_e32 v56, 16, v74
	v_and_b32_e32 v57, 0xffff0000, v74
	v_lshlrev_b32_e32 v58, 16, v75
	v_and_b32_e32 v59, 0xffff0000, v75
	v_lshlrev_b32_e32 v44, 16, v84
	v_and_b32_e32 v45, 0xffff0000, v84
	v_lshlrev_b32_e32 v46, 16, v85
	v_and_b32_e32 v47, 0xffff0000, v85
	v_pk_add_f32 v[54:55], v[54:55], v[58:59]
	v_pk_add_f32 v[52:53], v[52:53], v[56:57]
	v_pk_add_f32 v[34:35], v[34:35], v[46:47]
	v_pk_add_f32 v[32:33], v[32:33], v[44:45]
	global_store_dwordx4 v[70:71], v[52:55], off offset:512
	global_store_dwordx4 v[48:49], v[32:35], off offset:528
	s_nop 0
	v_lshlrev_b32_e32 v52, 16, v80
	v_and_b32_e32 v53, 0xffff0000, v80
	v_lshlrev_b32_e32 v54, 16, v81
	v_and_b32_e32 v55, 0xffff0000, v81
	v_lshlrev_b32_e32 v32, 16, v86
	v_and_b32_e32 v33, 0xffff0000, v86
	v_pk_add_f32 v[42:43], v[42:43], v[54:55]
	v_pk_add_f32 v[40:41], v[40:41], v[52:53]
	v_pk_add_f32 v[28:29], v[28:29], v[32:33]
	v_lshlrev_b64 v[32:33], 12, v[102:103]
	global_store_dwordx4 v[48:49], v[40:43], off offset:16
	v_lshlrev_b32_e32 v34, 16, v87
	v_and_b32_e32 v35, 0xffff0000, v87
	v_lshlrev_b32_e32 v40, 16, v82
	v_and_b32_e32 v41, 0xffff0000, v82
	v_lshlrev_b32_e32 v42, 16, v83
	v_and_b32_e32 v43, 0xffff0000, v83
	v_lshl_add_u64 v[32:33], s[54:55], 0, v[32:33]
	v_pk_add_f32 v[38:39], v[38:39], v[42:43]
	v_pk_add_f32 v[36:37], v[36:37], v[40:41]
	v_pk_add_f32 v[30:31], v[30:31], v[34:35]
	v_lshl_add_u64 v[32:33], v[32:33], 0, v[144:145]
	global_store_dwordx4 v[48:49], v[36:39], off offset:512
	global_store_dwordx4 v[32:33], v[28:31], off
	s_nop 0
	v_lshlrev_b32_e32 v36, 16, v88
	v_and_b32_e32 v37, 0xffff0000, v88
	v_lshlrev_b32_e32 v38, 16, v89
	v_and_b32_e32 v39, 0xffff0000, v89
	v_lshlrev_b32_e32 v28, 16, v92
	v_and_b32_e32 v29, 0xffff0000, v92
	v_lshlrev_b32_e32 v30, 16, v93
	v_and_b32_e32 v31, 0xffff0000, v93
	v_pk_add_f32 v[26:27], v[26:27], v[38:39]
	v_pk_add_f32 v[24:25], v[24:25], v[36:37]
	v_pk_add_f32 v[18:19], v[18:19], v[30:31]
	v_pk_add_f32 v[16:17], v[16:17], v[28:29]
	global_store_dwordx4 v[32:33], v[24:27], off offset:16
	global_store_dwordx4 v[32:33], v[16:19], off offset:528
	s_nop 0
	v_lshlrev_b32_e32 v24, 16, v90
	v_and_b32_e32 v25, 0xffff0000, v90
	v_lshlrev_b32_e32 v26, 16, v91
	v_and_b32_e32 v27, 0xffff0000, v91
	v_lshlrev_b32_e32 v16, 16, v94
	v_and_b32_e32 v17, 0xffff0000, v94
	v_pk_add_f32 v[22:23], v[22:23], v[26:27]
	v_pk_add_f32 v[20:21], v[20:21], v[24:25]
	v_pk_add_f32 v[12:13], v[12:13], v[16:17]
	v_lshlrev_b64 v[16:17], 12, v[68:69]
	global_store_dwordx4 v[32:33], v[20:23], off offset:512
	v_lshlrev_b32_e32 v18, 16, v95
	v_and_b32_e32 v19, 0xffff0000, v95
	v_lshlrev_b32_e32 v20, 16, v96
	v_and_b32_e32 v21, 0xffff0000, v96
	v_lshlrev_b32_e32 v22, 16, v97
	v_and_b32_e32 v23, 0xffff0000, v97
	v_lshl_add_u64 v[16:17], s[54:55], 0, v[16:17]
	v_pk_add_f32 v[14:15], v[14:15], v[18:19]
	v_lshl_add_u64 v[16:17], v[16:17], 0, v[144:145]
	v_pk_add_f32 v[10:11], v[10:11], v[22:23]
	v_pk_add_f32 v[8:9], v[8:9], v[20:21]
	global_store_dwordx4 v[16:17], v[12:15], off
	global_store_dwordx4 v[16:17], v[8:11], off offset:16
	s_nop 0
	v_lshlrev_b32_e32 v12, 16, v66
	v_lshlrev_b32_e32 v8, 16, v64
	v_and_b32_e32 v9, 0xffff0000, v64
	v_lshlrev_b32_e32 v10, 16, v65
	v_and_b32_e32 v11, 0xffff0000, v65
	v_and_b32_e32 v13, 0xffff0000, v66
	v_lshlrev_b32_e32 v14, 16, v67
	v_and_b32_e32 v15, 0xffff0000, v67
	v_pk_add_f32 v[6:7], v[6:7], v[10:11]
	v_pk_add_f32 v[4:5], v[4:5], v[8:9]
	v_pk_add_f32 v[2:3], v[2:3], v[14:15]
	v_pk_add_f32 v[0:1], v[0:1], v[12:13]
	global_store_dwordx4 v[16:17], v[4:7], off offset:512
	global_store_dwordx4 v[16:17], v[0:3], off offset:528
	s_cbranch_vccnz .LBB0_901
; #define PG8_BAR __builtin_amdgcn_s_barrier()
; template <class Epi, class Sched, bool ALIGN_EPI = false, bool SP2 = false>
; __device__ __forceinline__ void gemm_phase(PG8_LAS unsigned char* lds, const Gemm g, const Sched& S, const Epi& E) {
;     ...
;         cur = nxt; cA = nA; cB = nB; ++ui;
;         if constexpr (ALIGN_EPI) { if (wr == 1) PG8_BAR; }
	s_andn2_b64 vcc, exec, s[14:15]
	s_cbranch_vccnz .LBB0_900
	s_barrier
	s_branch .LBB0_900
